# proj + 3 split-K gemm8: transposed accumulators + packed dwordx4 epilogue stores
# speedup vs baseline: 1.0307x; 1.0061x over previous
.LBB0_195:
	ds_read_b128 v[160:163], v196
	ds_read_b128 v[164:167], v198
	ds_read_b128 v[180:183], v198 offset:64
	ds_read_b128 v[168:171], v196 offset:64
	ds_read_b128 v[172:175], v198 offset:2304
	ds_read_b128 v[206:209], v198 offset:2368
	ds_read_b128 v[176:179], v198 offset:4608
	ds_read_b128 v[210:213], v198 offset:4672
	ds_read_b128 v[184:187], v198 offset:6912
	ds_read_b128 v[214:217], v198 offset:6976
	s_waitcnt lgkmcnt(8)
	v_mfma_f32_16x16x32_bf16 v[156:159], v[164:167], v[160:163], v[156:159]
	s_add_i32 s49, s49, 2
	s_add_u32 s50, s45, 0xffffff80
	s_addc_u32 s51, s48, -1
	s_waitcnt lgkmcnt(5)
	v_mfma_f32_16x16x32_bf16 v[152:155], v[172:175], v[160:163], v[152:155]
	s_add_u32 s56, s30, 0xffffff80
	s_addc_u32 s57, s31, -1
	s_cmp_gt_u32 s49, 13
	s_waitcnt lgkmcnt(3)
	v_mfma_f32_16x16x32_bf16 v[148:151], v[176:179], v[160:163], v[148:151]
	s_cselect_b64 s[4:5], -1, 0
	s_and_b64 vcc, s[4:5], exec
	s_cselect_b32 s5, s11, s51
	s_waitcnt lgkmcnt(1)
	v_mfma_f32_16x16x32_bf16 v[144:147], v[184:187], v[160:163], v[144:147]
	ds_read_b128 v[160:163], v196 offset:2304
	ds_read_b128 v[188:191], v196 offset:2368
	s_cselect_b32 s4, s10, s50
	s_cselect_b32 s51, s13, s57
	s_waitcnt lgkmcnt(1)
	v_mfma_f32_16x16x32_bf16 v[140:143], v[164:167], v[160:163], v[140:143]
	s_cselect_b32 s50, s12, s56
	s_cmp_gt_u32 s49, 12
	v_mfma_f32_16x16x32_bf16 v[136:139], v[172:175], v[160:163], v[136:139]
	v_mfma_f32_16x16x32_bf16 v[132:135], v[176:179], v[160:163], v[132:135]
	v_mfma_f32_16x16x32_bf16 v[128:131], v[184:187], v[160:163], v[128:131]
	ds_read_b128 v[160:163], v196 offset:4608
	ds_read_b128 v[218:221], v196 offset:4672
	s_waitcnt lgkmcnt(1)
	v_mfma_f32_16x16x32_bf16 v[124:127], v[164:167], v[160:163], v[124:127]
	v_mfma_f32_16x16x32_bf16 v[120:123], v[172:175], v[160:163], v[120:123]
	v_mfma_f32_16x16x32_bf16 v[116:119], v[176:179], v[160:163], v[116:119]
	v_mfma_f32_16x16x32_bf16 v[112:115], v[184:187], v[160:163], v[112:115]
	ds_read_b128 v[160:163], v196 offset:6912
	ds_read_b128 v[222:225], v196 offset:6976
	s_waitcnt lgkmcnt(1)
	v_mfma_f32_16x16x32_bf16 v[108:111], v[164:167], v[160:163], v[108:111]
	v_mfma_f32_16x16x32_bf16 v[104:107], v[172:175], v[160:163], v[104:107]
	v_mfma_f32_16x16x32_bf16 v[100:103], v[176:179], v[160:163], v[100:103]
	v_mfma_f32_16x16x32_bf16 v[96:99], v[184:187], v[160:163], v[96:99]
	ds_read_b128 v[160:163], v196 offset:9216
	ds_read_b128 v[226:229], v196 offset:9280
	s_waitcnt lgkmcnt(1)
	v_mfma_f32_16x16x32_bf16 v[92:95], v[164:167], v[160:163], v[92:95]
	v_mfma_f32_16x16x32_bf16 v[88:91], v[172:175], v[160:163], v[88:91]
	v_mfma_f32_16x16x32_bf16 v[84:87], v[176:179], v[160:163], v[84:87]
	v_mfma_f32_16x16x32_bf16 v[80:83], v[184:187], v[160:163], v[80:83]
	ds_read_b128 v[160:163], v196 offset:11520
	ds_read_b128 v[230:233], v196 offset:11584
	s_waitcnt lgkmcnt(1)
	v_mfma_f32_16x16x32_bf16 v[68:71], v[164:167], v[160:163], v[68:71]
	v_mfma_f32_16x16x32_bf16 v[64:67], v[172:175], v[160:163], v[64:67]
	v_mfma_f32_16x16x32_bf16 v[60:63], v[176:179], v[160:163], v[60:63]
	v_mfma_f32_16x16x32_bf16 v[56:59], v[184:187], v[160:163], v[56:59]
	ds_read_b128 v[160:163], v196 offset:13824
	ds_read_b128 v[234:237], v196 offset:13888
	s_waitcnt lgkmcnt(1)
	v_mfma_f32_16x16x32_bf16 v[52:55], v[164:167], v[160:163], v[52:55]
	v_mfma_f32_16x16x32_bf16 v[48:51], v[172:175], v[160:163], v[48:51]
	v_mfma_f32_16x16x32_bf16 v[44:47], v[176:179], v[160:163], v[44:47]
	v_mfma_f32_16x16x32_bf16 v[40:43], v[184:187], v[160:163], v[40:43]
	ds_read_b128 v[160:163], v196 offset:16128
	ds_read_b128 v[238:241], v196 offset:16192
	s_waitcnt vmcnt(6)
	ds_write_b128 v194, v[4:7] offset:36864
	s_waitcnt vmcnt(5)
	ds_write_b128 v194, v[8:11] offset:46080
	s_waitcnt vmcnt(4)
	ds_write_b128 v194, v[12:15] offset:55296
	s_waitcnt vmcnt(3)
	ds_write_b128 v194, v[16:19] offset:64512
	s_waitcnt vmcnt(3)
	ds_write_b128 v199, v[0:3]
	s_waitcnt vmcnt(2)
	ds_write_b128 v199, v[20:23] offset:9216
	v_mfma_f32_16x16x32_bf16 v[20:23], v[214:217], v[226:229], v[80:83]
	s_waitcnt vmcnt(1)
	ds_write_b128 v199, v[24:27] offset:18432
	s_waitcnt vmcnt(0)
	ds_write_b128 v199, v[28:31] offset:27648
	v_lshl_add_u64 v[80:81], s[4:5], 0, v[192:193]
	v_mfma_f32_16x16x32_bf16 v[24:27], v[180:183], v[230:233], v[68:71]
	v_lshl_add_u64 v[82:83], s[50:51], 0, v[192:193]
	s_cselect_b32 s51, s44, s31
	s_cselect_b32 s50, s43, s30
	v_add_co_u32_e64 v68, s[4:5], s14, v80
	v_mfma_f32_16x16x32_bf16 v[28:31], v[206:209], v[230:233], v[64:67]
	s_nop 0
	v_addc_co_u32_e64 v69, s[4:5], 0, v81, s[4:5]
	s_nop 0
	v_add_co_u32_e64 v64, s[4:5], s15, v80
	s_waitcnt lgkmcnt(9)
	v_mfma_f32_16x16x32_bf16 v[36:39], v[164:167], v[160:163], v[36:39]
	v_addc_co_u32_e64 v65, s[4:5], 0, v81, s[4:5]
	v_add_co_u32_e64 v66, s[4:5], s27, v80
	v_mfma_f32_16x16x32_bf16 v[32:35], v[172:175], v[160:163], v[32:35]
	s_nop 0
	v_addc_co_u32_e64 v67, s[4:5], 0, v81, s[4:5]
	v_add_co_u32_e64 v70, s[4:5], s14, v82
	v_mfma_f32_16x16x32_bf16 v[76:79], v[176:179], v[160:163], v[76:79]
	s_nop 0
	v_addc_co_u32_e64 v71, s[4:5], 0, v83, s[4:5]
	global_load_dwordx4 v[164:167], v[82:83], off
	v_mfma_f32_16x16x32_bf16 v[72:75], v[184:187], v[160:163], v[72:75]
	global_load_dwordx4 v[160:163], v[80:81], off
	v_add_co_u32_e64 v80, s[4:5], s15, v82
	v_mfma_f32_16x16x32_bf16 v[156:159], v[180:183], v[168:171], v[156:159]
	s_nop 0
	v_addc_co_u32_e64 v81, s[4:5], 0, v83, s[4:5]
	v_add_co_u32_e64 v82, s[4:5], s27, v82
	v_mfma_f32_16x16x32_bf16 v[152:155], v[206:209], v[168:171], v[152:155]
	s_nop 0
	v_addc_co_u32_e64 v83, s[4:5], 0, v83, s[4:5]
	s_cselect_b32 s5, s25, s48
	v_mfma_f32_16x16x32_bf16 v[148:151], v[210:213], v[168:171], v[148:151]
	s_cselect_b32 s4, s23, s45
	s_add_u32 s30, s30, 0x100
	s_addc_u32 s31, s31, 0
	v_mfma_f32_16x16x32_bf16 v[144:147], v[214:217], v[168:171], v[144:147]
	global_load_dwordx4 v[168:171], v[68:69], off
	global_load_dwordx4 v[172:175], v[64:65], off
	global_load_dwordx4 v[176:179], v[66:67], off
	s_add_u32 s45, s45, 0x100
	s_addc_u32 s48, s48, 0
	v_mfma_f32_16x16x32_bf16 v[140:143], v[180:183], v[188:191], v[140:143]
	v_mfma_f32_16x16x32_bf16 v[136:139], v[206:209], v[188:191], v[136:139]
	v_mfma_f32_16x16x32_bf16 v[132:135], v[210:213], v[188:191], v[132:135]
	v_mfma_f32_16x16x32_bf16 v[128:131], v[214:217], v[188:191], v[128:131]
	v_mfma_f32_16x16x32_bf16 v[124:127], v[180:183], v[218:221], v[124:127]
	v_mfma_f32_16x16x32_bf16 v[108:111], v[180:183], v[222:225], v[108:111]
	v_mfma_f32_16x16x32_bf16 v[8:11], v[180:183], v[226:229], v[92:95]
	v_mfma_f32_16x16x32_bf16 v[52:55], v[180:183], v[234:237], v[52:55]
	s_waitcnt lgkmcnt(8)
	v_mfma_f32_16x16x32_bf16 v[36:39], v[180:183], v[238:241], v[36:39]
	global_load_dwordx4 v[180:183], v[70:71], off
	global_load_dwordx4 v[184:187], v[80:81], off
	global_load_dwordx4 v[188:191], v[82:83], off
	s_waitcnt lgkmcnt(0)
	s_barrier
	ds_read_b128 v[68:71], v196 offset:36864
	v_mfma_f32_16x16x32_bf16 v[120:123], v[206:209], v[218:221], v[120:123]
	v_mfma_f32_16x16x32_bf16 v[116:119], v[210:213], v[218:221], v[116:119]
	v_mfma_f32_16x16x32_bf16 v[104:107], v[206:209], v[222:225], v[104:107]
	v_mfma_f32_16x16x32_bf16 v[4:7], v[210:213], v[222:225], v[100:103]
	v_mfma_f32_16x16x32_bf16 v[0:3], v[214:217], v[222:225], v[96:99]
	v_mfma_f32_16x16x32_bf16 v[12:15], v[206:209], v[226:229], v[88:91]
	v_mfma_f32_16x16x32_bf16 v[16:19], v[210:213], v[226:229], v[84:87]
	v_mfma_f32_16x16x32_bf16 v[60:63], v[210:213], v[230:233], v[60:63]
	v_mfma_f32_16x16x32_bf16 v[48:51], v[206:209], v[234:237], v[48:51]
	v_mfma_f32_16x16x32_bf16 v[44:47], v[210:213], v[234:237], v[44:47]
	v_mfma_f32_16x16x32_bf16 v[32:35], v[206:209], v[238:241], v[32:35]
	ds_read_b128 v[84:87], v200
	ds_read_b128 v[206:209], v200 offset:64
	ds_read_b128 v[88:91], v196 offset:36928
	v_mfma_f32_16x16x32_bf16 v[64:67], v[210:213], v[238:241], v[76:79]
	ds_read_b128 v[96:99], v200 offset:2304
	ds_read_b128 v[210:213], v200 offset:2368
	v_mfma_f32_16x16x32_bf16 v[80:83], v[214:217], v[238:241], v[72:75]
	s_waitcnt lgkmcnt(4)
	v_mfma_f32_16x16x32_bf16 v[92:95], v[84:87], v[68:71], v[156:159]
	s_waitcnt lgkmcnt(1)
	v_mfma_f32_16x16x32_bf16 v[100:103], v[96:99], v[68:71], v[152:155]
	s_nop 2
	ds_read_b128 v[152:155], v200 offset:4608
	ds_read_b128 v[76:79], v200 offset:4672
	ds_read_b128 v[156:159], v200 offset:6912
	ds_read_b128 v[72:75], v200 offset:6976
	v_mfma_f32_16x16x32_bf16 v[112:115], v[214:217], v[218:221], v[112:115]
	v_mfma_f32_16x16x32_bf16 v[56:59], v[214:217], v[230:233], v[56:59]
	v_mfma_f32_16x16x32_bf16 v[40:43], v[214:217], v[234:237], v[40:43]
	s_waitcnt lgkmcnt(3)
	v_mfma_f32_16x16x32_bf16 v[148:151], v[152:155], v[68:71], v[148:151]
	s_waitcnt lgkmcnt(1)
	v_mfma_f32_16x16x32_bf16 v[68:71], v[156:159], v[68:71], v[144:147]
	s_nop 2
	ds_read_b128 v[144:147], v196 offset:39168
	ds_read_b128 v[214:217], v196 offset:39232
	s_waitcnt lgkmcnt(1)
	v_mfma_f32_16x16x32_bf16 v[140:143], v[84:87], v[144:147], v[140:143]
	v_mfma_f32_16x16x32_bf16 v[136:139], v[96:99], v[144:147], v[136:139]
	v_mfma_f32_16x16x32_bf16 v[132:135], v[152:155], v[144:147], v[132:135]
	v_mfma_f32_16x16x32_bf16 v[128:131], v[156:159], v[144:147], v[128:131]
	ds_read_b128 v[144:147], v196 offset:41472
	ds_read_b128 v[218:221], v196 offset:41536
	s_waitcnt lgkmcnt(1)
	v_mfma_f32_16x16x32_bf16 v[124:127], v[84:87], v[144:147], v[124:127]
	v_mfma_f32_16x16x32_bf16 v[120:123], v[96:99], v[144:147], v[120:123]
	v_mfma_f32_16x16x32_bf16 v[116:119], v[152:155], v[144:147], v[116:119]
	v_mfma_f32_16x16x32_bf16 v[112:115], v[156:159], v[144:147], v[112:115]
	ds_read_b128 v[144:147], v196 offset:43776
	ds_read_b128 v[222:225], v196 offset:43840
	s_waitcnt lgkmcnt(1)
	v_mfma_f32_16x16x32_bf16 v[108:111], v[84:87], v[144:147], v[108:111]
	v_mfma_f32_16x16x32_bf16 v[104:107], v[96:99], v[144:147], v[104:107]
	v_mfma_f32_16x16x32_bf16 v[4:7], v[152:155], v[144:147], v[4:7]
	v_mfma_f32_16x16x32_bf16 v[0:3], v[156:159], v[144:147], v[0:3]
	ds_read_b128 v[144:147], v196 offset:46080
	ds_read_b128 v[226:229], v196 offset:46144
	s_waitcnt lgkmcnt(1)
	v_mfma_f32_16x16x32_bf16 v[8:11], v[84:87], v[144:147], v[8:11]
	v_mfma_f32_16x16x32_bf16 v[12:15], v[96:99], v[144:147], v[12:15]
	v_mfma_f32_16x16x32_bf16 v[16:19], v[152:155], v[144:147], v[16:19]
	v_mfma_f32_16x16x32_bf16 v[20:23], v[156:159], v[144:147], v[20:23]
	ds_read_b128 v[144:147], v196 offset:48384
	ds_read_b128 v[230:233], v196 offset:48448
	s_waitcnt lgkmcnt(1)
	v_mfma_f32_16x16x32_bf16 v[24:27], v[84:87], v[144:147], v[24:27]
	v_mfma_f32_16x16x32_bf16 v[28:31], v[96:99], v[144:147], v[28:31]
	v_mfma_f32_16x16x32_bf16 v[60:63], v[152:155], v[144:147], v[60:63]
	v_mfma_f32_16x16x32_bf16 v[56:59], v[156:159], v[144:147], v[56:59]
	ds_read_b128 v[144:147], v196 offset:50688
	ds_read_b128 v[234:237], v196 offset:50752
	s_waitcnt lgkmcnt(1)
	v_mfma_f32_16x16x32_bf16 v[52:55], v[84:87], v[144:147], v[52:55]
	v_mfma_f32_16x16x32_bf16 v[48:51], v[96:99], v[144:147], v[48:51]
	v_mfma_f32_16x16x32_bf16 v[44:47], v[152:155], v[144:147], v[44:47]
	v_mfma_f32_16x16x32_bf16 v[40:43], v[156:159], v[144:147], v[40:43]
	ds_read_b128 v[144:147], v196 offset:52992
	ds_read_b128 v[238:241], v196 offset:53056
	s_waitcnt lgkmcnt(1)
	v_mfma_f32_16x16x32_bf16 v[242:245], v[152:155], v[144:147], v[64:67]
	v_mfma_f32_16x16x32_bf16 v[152:155], v[210:213], v[88:91], v[100:103]
	v_mfma_f32_16x16x32_bf16 v[100:103], v[76:79], v[222:225], v[4:7]
	s_nop 2
	v_lshl_add_u64 v[4:5], s[4:5], 0, v[192:193]
	v_mfma_f32_16x16x32_bf16 v[246:249], v[156:159], v[144:147], v[80:83]
	v_lshl_add_u64 v[6:7], s[50:51], 0, v[192:193]
	v_mfma_f32_16x16x32_bf16 v[156:159], v[206:209], v[88:91], v[92:95]
	v_mfma_f32_16x16x32_bf16 v[92:95], v[206:209], v[226:229], v[8:11]
	s_nop 2
	v_add_co_u32_e64 v8, s[4:5], s14, v4
	v_mfma_f32_16x16x32_bf16 v[36:39], v[84:87], v[144:147], v[36:39]
	s_nop 0
	v_addc_co_u32_e64 v9, s[4:5], 0, v5, s[4:5]
	v_mfma_f32_16x16x32_bf16 v[32:35], v[96:99], v[144:147], v[32:35]
	v_mfma_f32_16x16x32_bf16 v[148:151], v[76:79], v[88:91], v[148:151]
	v_mfma_f32_16x16x32_bf16 v[144:147], v[72:75], v[88:91], v[68:71]
	v_mfma_f32_16x16x32_bf16 v[88:91], v[210:213], v[226:229], v[12:15]
	s_nop 2
	v_add_co_u32_e64 v12, s[4:5], s15, v4
	v_mfma_f32_16x16x32_bf16 v[84:87], v[76:79], v[226:229], v[16:19]
	s_nop 0
	v_addc_co_u32_e64 v13, s[4:5], 0, v5, s[4:5]
	s_nop 0
	v_add_co_u32_e64 v16, s[4:5], s27, v4
	v_mfma_f32_16x16x32_bf16 v[80:83], v[72:75], v[226:229], v[20:23]
	s_nop 0
	v_addc_co_u32_e64 v17, s[4:5], 0, v5, s[4:5]
	s_nop 0
	v_add_co_u32_e64 v20, s[4:5], s14, v6
	v_mfma_f32_16x16x32_bf16 v[68:71], v[206:209], v[230:233], v[24:27]
	s_nop 0
	v_addc_co_u32_e64 v21, s[4:5], 0, v7, s[4:5]
	s_nop 0
	v_add_co_u32_e64 v24, s[4:5], s15, v6
	v_mfma_f32_16x16x32_bf16 v[64:67], v[210:213], v[230:233], v[28:31]
	s_nop 0
	v_addc_co_u32_e64 v25, s[4:5], 0, v7, s[4:5]
	s_nop 0
	v_add_co_u32_e64 v28, s[4:5], s27, v6
	v_mfma_f32_16x16x32_bf16 v[96:99], v[72:75], v[222:225], v[0:3]
	s_nop 0
	v_addc_co_u32_e64 v29, s[4:5], 0, v7, s[4:5]
	s_nop 0
	global_load_dwordx4 v[0:3], v[6:7], off
	s_nop 0
	global_load_dwordx4 v[4:7], v[4:5], off
	s_nop 0
	global_load_dwordx4 v[8:11], v[8:9], off
	s_nop 0
	global_load_dwordx4 v[12:15], v[12:13], off
	s_nop 0
	global_load_dwordx4 v[16:19], v[16:17], off
	s_nop 0
	global_load_dwordx4 v[20:23], v[20:21], off
	s_nop 0
	global_load_dwordx4 v[24:27], v[24:25], off
	v_mfma_f32_16x16x32_bf16 v[140:143], v[206:209], v[214:217], v[140:143]
	global_load_dwordx4 v[28:31], v[28:29], off
	s_waitcnt vmcnt(14)
	ds_write_b128 v194, v[160:163]
	ds_write_b128 v195, v[164:167]
	s_waitcnt vmcnt(13)
	ds_write_b128 v194, v[168:171] offset:9216
	s_waitcnt vmcnt(12)
	ds_write_b128 v194, v[172:175] offset:18432
	s_waitcnt vmcnt(11)
	ds_write_b128 v194, v[176:179] offset:27648
	s_waitcnt vmcnt(10)
	ds_write_b128 v195, v[180:183] offset:9216
	s_waitcnt vmcnt(9)
	ds_write_b128 v195, v[184:187] offset:18432
	s_waitcnt vmcnt(8)
	ds_write_b128 v195, v[188:191] offset:27648
	s_waitcnt lgkmcnt(0)
	v_mfma_f32_16x16x32_bf16 v[136:139], v[210:213], v[214:217], v[136:139]
	s_barrier
	v_mfma_f32_16x16x32_bf16 v[132:135], v[76:79], v[214:217], v[132:135]
	v_mfma_f32_16x16x32_bf16 v[128:131], v[72:75], v[214:217], v[128:131]
	v_mfma_f32_16x16x32_bf16 v[124:127], v[206:209], v[218:221], v[124:127]
	v_mfma_f32_16x16x32_bf16 v[120:123], v[210:213], v[218:221], v[120:123]
	v_mfma_f32_16x16x32_bf16 v[116:119], v[76:79], v[218:221], v[116:119]
	v_mfma_f32_16x16x32_bf16 v[112:115], v[72:75], v[218:221], v[112:115]
	v_mfma_f32_16x16x32_bf16 v[108:111], v[206:209], v[222:225], v[108:111]
	v_mfma_f32_16x16x32_bf16 v[104:107], v[210:213], v[222:225], v[104:107]
	v_mfma_f32_16x16x32_bf16 v[60:63], v[76:79], v[230:233], v[60:63]
	v_mfma_f32_16x16x32_bf16 v[56:59], v[72:75], v[230:233], v[56:59]
	v_mfma_f32_16x16x32_bf16 v[52:55], v[206:209], v[234:237], v[52:55]
	v_mfma_f32_16x16x32_bf16 v[48:51], v[210:213], v[234:237], v[48:51]
	v_mfma_f32_16x16x32_bf16 v[44:47], v[76:79], v[234:237], v[44:47]
	v_mfma_f32_16x16x32_bf16 v[40:43], v[72:75], v[234:237], v[40:43]
	v_mfma_f32_16x16x32_bf16 v[36:39], v[206:209], v[238:241], v[36:39]
	v_mfma_f32_16x16x32_bf16 v[32:35], v[210:213], v[238:241], v[32:35]
	v_mfma_f32_16x16x32_bf16 v[76:79], v[76:79], v[238:241], v[242:245]
	v_mfma_f32_16x16x32_bf16 v[72:75], v[72:75], v[238:241], v[246:249]
	s_cbranch_vccz .LBB0_195
	s_mul_i32 s98, s26, 0x1040
	s_lshl_b32 s99, s28, 1
	s_add_u32 s98, s98, s99
	s_add_u32 s100, s16, s98
	s_addc_u32 s101, s17, 0
	v_and_b32_e32 v160, 15, v197
	v_and_b32_e32 v161, 0x80, v201
	v_add_u32_e32 v160, v160, v161
	v_mul_u32_u24_e32 v160, 0x1040, v160
	v_and_b32_e32 v161, 0xc0, v197
	v_lshl_add_u32 v160, v161, 1, v160
	v_and_b32_e32 v161, 4, v201
	v_lshl_add_u32 v160, v161, 3, v160
	v_and_b32_e32 v161, 8, v201
	v_lshl_add_u32 v160, v161, 1, v160
	v_cvt_pk_bf16_f32 v156, v156, v157
	v_cvt_pk_bf16_f32 v157, v158, v159
	v_cvt_pk_bf16_f32 v158, v152, v153
	v_cvt_pk_bf16_f32 v159, v154, v155
	v_cvt_pk_bf16_f32 v148, v148, v149
	v_cvt_pk_bf16_f32 v149, v150, v151
	v_cvt_pk_bf16_f32 v150, v144, v145
	v_cvt_pk_bf16_f32 v151, v146, v147
	v_permlane16_swap_b32_e32 v156, v158
	v_permlane16_swap_b32_e32 v157, v159
	v_permlane16_swap_b32_e32 v148, v150
	v_permlane16_swap_b32_e32 v149, v151
	global_store_dwordx4 v160, v[156:159], s[100:101]
	global_store_dwordx4 v160, v[148:151], s[100:101] offset:64
	s_add_u32 s100, s100, 0x10400
	s_addc_u32 s101, s101, 0
	v_cvt_pk_bf16_f32 v140, v140, v141
	v_cvt_pk_bf16_f32 v141, v142, v143
	v_cvt_pk_bf16_f32 v142, v136, v137
	v_cvt_pk_bf16_f32 v143, v138, v139
	v_cvt_pk_bf16_f32 v132, v132, v133
	v_cvt_pk_bf16_f32 v133, v134, v135
	v_cvt_pk_bf16_f32 v134, v128, v129
	v_cvt_pk_bf16_f32 v135, v130, v131
	v_permlane16_swap_b32_e32 v140, v142
	v_permlane16_swap_b32_e32 v141, v143
	v_permlane16_swap_b32_e32 v132, v134
	v_permlane16_swap_b32_e32 v133, v135
	global_store_dwordx4 v160, v[140:143], s[100:101]
	global_store_dwordx4 v160, v[132:135], s[100:101] offset:64
	s_add_u32 s100, s100, 0x10400
	s_addc_u32 s101, s101, 0
	v_cvt_pk_bf16_f32 v124, v124, v125
	v_cvt_pk_bf16_f32 v125, v126, v127
	v_cvt_pk_bf16_f32 v126, v120, v121
	v_cvt_pk_bf16_f32 v127, v122, v123
	v_cvt_pk_bf16_f32 v116, v116, v117
	v_cvt_pk_bf16_f32 v117, v118, v119
	v_cvt_pk_bf16_f32 v118, v112, v113
	v_cvt_pk_bf16_f32 v119, v114, v115
	v_permlane16_swap_b32_e32 v124, v126
	v_permlane16_swap_b32_e32 v125, v127
	v_permlane16_swap_b32_e32 v116, v118
	v_permlane16_swap_b32_e32 v117, v119
	global_store_dwordx4 v160, v[124:127], s[100:101]
	global_store_dwordx4 v160, v[116:119], s[100:101] offset:64
	s_add_u32 s100, s100, 0x10400
	s_addc_u32 s101, s101, 0
	v_cvt_pk_bf16_f32 v108, v108, v109
	v_cvt_pk_bf16_f32 v109, v110, v111
	v_cvt_pk_bf16_f32 v110, v104, v105
	v_cvt_pk_bf16_f32 v111, v106, v107
	v_cvt_pk_bf16_f32 v100, v100, v101
	v_cvt_pk_bf16_f32 v101, v102, v103
	v_cvt_pk_bf16_f32 v102, v96, v97
	v_cvt_pk_bf16_f32 v103, v98, v99
	v_permlane16_swap_b32_e32 v108, v110
	v_permlane16_swap_b32_e32 v109, v111
	v_permlane16_swap_b32_e32 v100, v102
	v_permlane16_swap_b32_e32 v101, v103
	global_store_dwordx4 v160, v[108:111], s[100:101]
	global_store_dwordx4 v160, v[100:103], s[100:101] offset:64
	s_add_u32 s100, s100, 0x10400
	s_addc_u32 s101, s101, 0
	v_cvt_pk_bf16_f32 v92, v92, v93
	v_cvt_pk_bf16_f32 v93, v94, v95
	v_cvt_pk_bf16_f32 v94, v88, v89
	v_cvt_pk_bf16_f32 v95, v90, v91
	v_cvt_pk_bf16_f32 v84, v84, v85
	v_cvt_pk_bf16_f32 v85, v86, v87
	v_cvt_pk_bf16_f32 v86, v80, v81
	v_cvt_pk_bf16_f32 v87, v82, v83
	v_permlane16_swap_b32_e32 v92, v94
	v_permlane16_swap_b32_e32 v93, v95
	v_permlane16_swap_b32_e32 v84, v86
	v_permlane16_swap_b32_e32 v85, v87
	global_store_dwordx4 v160, v[92:95], s[100:101]
	global_store_dwordx4 v160, v[84:87], s[100:101] offset:64
	s_add_u32 s100, s100, 0x10400
	s_addc_u32 s101, s101, 0
	v_cvt_pk_bf16_f32 v68, v68, v69
	v_cvt_pk_bf16_f32 v69, v70, v71
	v_cvt_pk_bf16_f32 v70, v64, v65
	v_cvt_pk_bf16_f32 v71, v66, v67
	v_cvt_pk_bf16_f32 v60, v60, v61
	v_cvt_pk_bf16_f32 v61, v62, v63
	v_cvt_pk_bf16_f32 v62, v56, v57
	v_cvt_pk_bf16_f32 v63, v58, v59
	v_permlane16_swap_b32_e32 v68, v70
	v_permlane16_swap_b32_e32 v69, v71
	v_permlane16_swap_b32_e32 v60, v62
	v_permlane16_swap_b32_e32 v61, v63
	global_store_dwordx4 v160, v[68:71], s[100:101]
	global_store_dwordx4 v160, v[60:63], s[100:101] offset:64
	s_add_u32 s100, s100, 0x10400
	s_addc_u32 s101, s101, 0
	v_cvt_pk_bf16_f32 v52, v52, v53
	v_cvt_pk_bf16_f32 v53, v54, v55
	v_cvt_pk_bf16_f32 v54, v48, v49
	v_cvt_pk_bf16_f32 v55, v50, v51
	v_cvt_pk_bf16_f32 v44, v44, v45
	v_cvt_pk_bf16_f32 v45, v46, v47
	v_cvt_pk_bf16_f32 v46, v40, v41
	v_cvt_pk_bf16_f32 v47, v42, v43
	v_permlane16_swap_b32_e32 v52, v54
	v_permlane16_swap_b32_e32 v53, v55
	v_permlane16_swap_b32_e32 v44, v46
	v_permlane16_swap_b32_e32 v45, v47
	global_store_dwordx4 v160, v[52:55], s[100:101]
	global_store_dwordx4 v160, v[44:47], s[100:101] offset:64
	s_add_u32 s100, s100, 0x10400
	s_addc_u32 s101, s101, 0
	v_cvt_pk_bf16_f32 v36, v36, v37
	v_cvt_pk_bf16_f32 v37, v38, v39
	v_cvt_pk_bf16_f32 v38, v32, v33
	v_cvt_pk_bf16_f32 v39, v34, v35
	v_cvt_pk_bf16_f32 v76, v76, v77
	v_cvt_pk_bf16_f32 v77, v78, v79
	v_cvt_pk_bf16_f32 v78, v72, v73
	v_cvt_pk_bf16_f32 v79, v74, v75
	v_permlane16_swap_b32_e32 v36, v38
	v_permlane16_swap_b32_e32 v37, v39
	v_permlane16_swap_b32_e32 v76, v78
	v_permlane16_swap_b32_e32 v77, v79
	global_store_dwordx4 v160, v[36:39], s[100:101]
	global_store_dwordx4 v160, v[76:79], s[100:101] offset:64
	s_and_b64 vcc, exec, s[20:21]
	s_mov_b32 s28, s24
	s_mov_b32 s26, s22
	s_mov_b64 s[30:31], s[12:13]
	s_mov_b64 s[4:5], s[10:11]
	s_cbranch_vccz .LBB0_192

.LBB0_1020:
	ds_read_b128 v[160:163], v202
	ds_read_b128 v[164:167], v203
	ds_read_b128 v[180:183], v203 offset:64
	ds_read_b128 v[168:171], v202 offset:64
	ds_read_b128 v[172:175], v203 offset:2304
	ds_read_b128 v[192:195], v203 offset:2368
	ds_read_b128 v[176:179], v203 offset:4608
	ds_read_b128 v[210:213], v203 offset:4672
	ds_read_b128 v[184:187], v203 offset:6912
	ds_read_b128 v[214:217], v203 offset:6976
	s_waitcnt lgkmcnt(8)
	v_mfma_f32_16x16x32_bf16 v[156:159], v[164:167], v[160:163], v[156:159]
	s_add_i32 s81, s80, 2
	s_add_u32 s82, s58, 0xffffff80
	s_addc_u32 s83, s59, -1
	s_waitcnt lgkmcnt(5)
	v_mfma_f32_16x16x32_bf16 v[152:155], v[172:175], v[160:163], v[152:155]
	s_add_u32 s84, s60, 0xffffff80
	s_addc_u32 s85, s61, -1
	s_cmp_lt_u32 s80, 6
	s_waitcnt lgkmcnt(3)
	v_mfma_f32_16x16x32_bf16 v[148:151], v[176:179], v[160:163], v[148:151]
	s_cselect_b32 s82, s82, s42
	s_cselect_b32 s83, s83, s43
	s_cselect_b32 s84, s84, s44
	s_waitcnt lgkmcnt(1)
	v_mfma_f32_16x16x32_bf16 v[144:147], v[184:187], v[160:163], v[144:147]
	ds_read_b128 v[160:163], v202 offset:2304
	ds_read_b128 v[188:191], v202 offset:2368
	s_cselect_b32 s85, s85, s45
	s_cmp_lt_u32 s80, 5
	s_waitcnt lgkmcnt(1)
	v_mfma_f32_16x16x32_bf16 v[140:143], v[164:167], v[160:163], v[140:143]
	v_mfma_f32_16x16x32_bf16 v[136:139], v[172:175], v[160:163], v[136:139]
	v_mfma_f32_16x16x32_bf16 v[132:135], v[176:179], v[160:163], v[132:135]
	v_mfma_f32_16x16x32_bf16 v[128:131], v[184:187], v[160:163], v[128:131]
	ds_read_b128 v[160:163], v202 offset:4608
	ds_read_b128 v[218:221], v202 offset:4672
	s_waitcnt lgkmcnt(1)
	v_mfma_f32_16x16x32_bf16 v[124:127], v[164:167], v[160:163], v[124:127]
	v_mfma_f32_16x16x32_bf16 v[120:123], v[172:175], v[160:163], v[120:123]
	v_mfma_f32_16x16x32_bf16 v[116:119], v[176:179], v[160:163], v[116:119]
	v_mfma_f32_16x16x32_bf16 v[112:115], v[184:187], v[160:163], v[112:115]
	ds_read_b128 v[160:163], v202 offset:6912
	ds_read_b128 v[222:225], v202 offset:6976
	s_waitcnt lgkmcnt(1)
	v_mfma_f32_16x16x32_bf16 v[108:111], v[164:167], v[160:163], v[108:111]
	v_mfma_f32_16x16x32_bf16 v[104:107], v[172:175], v[160:163], v[104:107]
	v_mfma_f32_16x16x32_bf16 v[100:103], v[176:179], v[160:163], v[100:103]
	v_mfma_f32_16x16x32_bf16 v[96:99], v[184:187], v[160:163], v[96:99]
	ds_read_b128 v[160:163], v202 offset:9216
	ds_read_b128 v[226:229], v202 offset:9280
	s_waitcnt lgkmcnt(1)
	v_mfma_f32_16x16x32_bf16 v[92:95], v[164:167], v[160:163], v[92:95]
	v_mfma_f32_16x16x32_bf16 v[88:91], v[172:175], v[160:163], v[88:91]
	v_mfma_f32_16x16x32_bf16 v[80:83], v[176:179], v[160:163], v[80:83]
	v_mfma_f32_16x16x32_bf16 v[84:87], v[184:187], v[160:163], v[84:87]
	ds_read_b128 v[160:163], v202 offset:11520
	ds_read_b128 v[230:233], v202 offset:11584
	s_waitcnt lgkmcnt(1)
	v_mfma_f32_16x16x32_bf16 v[76:79], v[164:167], v[160:163], v[76:79]
	v_mfma_f32_16x16x32_bf16 v[72:75], v[172:175], v[160:163], v[72:75]
	v_mfma_f32_16x16x32_bf16 v[68:71], v[176:179], v[160:163], v[68:71]
	v_mfma_f32_16x16x32_bf16 v[64:67], v[184:187], v[160:163], v[64:67]
	ds_read_b128 v[160:163], v202 offset:13824
	ds_read_b128 v[234:237], v202 offset:13888
	s_waitcnt lgkmcnt(1)
	v_mfma_f32_16x16x32_bf16 v[60:63], v[164:167], v[160:163], v[60:63]
	v_mfma_f32_16x16x32_bf16 v[56:59], v[172:175], v[160:163], v[56:59]
	v_mfma_f32_16x16x32_bf16 v[52:55], v[176:179], v[160:163], v[52:55]
	v_mfma_f32_16x16x32_bf16 v[48:51], v[184:187], v[160:163], v[48:51]
	ds_read_b128 v[160:163], v202 offset:16128
	ds_read_b128 v[238:241], v202 offset:16192
	s_waitcnt vmcnt(6)
	ds_write_b128 v200, v[4:7] offset:36864
	s_waitcnt vmcnt(5)
	ds_write_b128 v200, v[8:11] offset:46080
	s_waitcnt vmcnt(4)
	ds_write_b128 v200, v[12:15] offset:55296
	s_waitcnt vmcnt(3)
	ds_write_b128 v200, v[16:19] offset:64512
	v_mfma_f32_16x16x32_bf16 v[16:19], v[210:213], v[226:229], v[80:83]
	s_waitcnt vmcnt(3)
	ds_write_b128 v208, v[0:3]
	s_waitcnt vmcnt(2)
	ds_write_b128 v208, v[20:23] offset:9216
	s_waitcnt vmcnt(1)
	ds_write_b128 v208, v[24:27] offset:18432
	v_lshl_add_u64 v[80:81], s[82:83], 0, v[196:197]
	s_waitcnt vmcnt(0)
	ds_write_b128 v208, v[28:31] offset:27648
	v_mfma_f32_16x16x32_bf16 v[24:27], v[180:183], v[230:233], v[76:79]
	v_lshl_add_u64 v[82:83], s[84:85], 0, v[196:197]
	s_cselect_b32 s82, s58, s49
	s_cselect_b32 s83, s59, s77
	v_add_co_u32_e32 v76, vcc, s57, v80
	v_mfma_f32_16x16x32_bf16 v[28:31], v[192:195], v[230:233], v[72:75]
	s_nop 0
	v_addc_co_u32_e32 v77, vcc, 0, v81, vcc
	s_cselect_b32 s84, s60, s78
	v_add_co_u32_e32 v72, vcc, s63, v80
	s_waitcnt lgkmcnt(9)
	v_mfma_f32_16x16x32_bf16 v[40:43], v[164:167], v[160:163], v[40:43]
	v_addc_co_u32_e32 v73, vcc, 0, v81, vcc
	v_add_co_u32_e32 v74, vcc, s64, v80
	v_mfma_f32_16x16x32_bf16 v[36:39], v[172:175], v[160:163], v[36:39]
	s_nop 0
	v_addc_co_u32_e32 v75, vcc, 0, v81, vcc
	v_add_co_u32_e32 v78, vcc, s57, v82
	v_mfma_f32_16x16x32_bf16 v[32:35], v[176:179], v[160:163], v[32:35]
	s_nop 0
	v_addc_co_u32_e32 v79, vcc, 0, v83, vcc
	global_load_dwordx4 v[164:167], v[82:83], off
	v_mfma_f32_16x16x32_bf16 v[44:47], v[184:187], v[160:163], v[44:47]
	global_load_dwordx4 v[160:163], v[80:81], off
	v_add_co_u32_e32 v80, vcc, s63, v82
	v_mfma_f32_16x16x32_bf16 v[156:159], v[180:183], v[168:171], v[156:159]
	s_nop 0
	v_addc_co_u32_e32 v81, vcc, 0, v83, vcc
	v_add_co_u32_e32 v82, vcc, s64, v82
	v_mfma_f32_16x16x32_bf16 v[152:155], v[192:195], v[168:171], v[152:155]
	s_nop 0
	v_addc_co_u32_e32 v83, vcc, 0, v83, vcc
	s_cselect_b32 s85, s61, s79
	v_mfma_f32_16x16x32_bf16 v[148:151], v[210:213], v[168:171], v[148:151]
	s_add_u32 s60, s60, 0x100
	s_addc_u32 s61, s61, 0
	s_add_u32 s58, s58, 0x100
	v_mfma_f32_16x16x32_bf16 v[144:147], v[214:217], v[168:171], v[144:147]
	global_load_dwordx4 v[168:171], v[76:77], off
	global_load_dwordx4 v[172:175], v[72:73], off
	global_load_dwordx4 v[176:179], v[74:75], off
	s_addc_u32 s59, s59, 0
	s_cmp_gt_u32 s80, 5
	v_mfma_f32_16x16x32_bf16 v[140:143], v[180:183], v[188:191], v[140:143]
	s_mov_b32 s80, s81
	v_mfma_f32_16x16x32_bf16 v[136:139], v[192:195], v[188:191], v[136:139]
	v_mfma_f32_16x16x32_bf16 v[132:135], v[210:213], v[188:191], v[132:135]
	v_mfma_f32_16x16x32_bf16 v[128:131], v[214:217], v[188:191], v[128:131]
	v_mfma_f32_16x16x32_bf16 v[124:127], v[180:183], v[218:221], v[124:127]
	v_mfma_f32_16x16x32_bf16 v[108:111], v[180:183], v[222:225], v[108:111]
	v_mfma_f32_16x16x32_bf16 v[0:3], v[180:183], v[226:229], v[92:95]
	v_mfma_f32_16x16x32_bf16 v[60:63], v[180:183], v[234:237], v[60:63]
	s_waitcnt lgkmcnt(8)
	v_mfma_f32_16x16x32_bf16 v[40:43], v[180:183], v[238:241], v[40:43]
	global_load_dwordx4 v[180:183], v[78:79], off
	global_load_dwordx4 v[184:187], v[80:81], off
	global_load_dwordx4 v[188:191], v[82:83], off
	s_waitcnt lgkmcnt(0)
	s_barrier
	ds_read_b128 v[72:75], v202 offset:36864
	v_mfma_f32_16x16x32_bf16 v[116:119], v[210:213], v[218:221], v[116:119]
	v_mfma_f32_16x16x32_bf16 v[112:115], v[214:217], v[218:221], v[112:115]
	v_mfma_f32_16x16x32_bf16 v[4:7], v[210:213], v[222:225], v[100:103]
	v_mfma_f32_16x16x32_bf16 v[8:11], v[214:217], v[222:225], v[96:99]
	v_mfma_f32_16x16x32_bf16 v[20:23], v[214:217], v[226:229], v[84:87]
	v_mfma_f32_16x16x32_bf16 v[68:71], v[210:213], v[230:233], v[68:71]
	v_mfma_f32_16x16x32_bf16 v[64:67], v[214:217], v[230:233], v[64:67]
	v_mfma_f32_16x16x32_bf16 v[52:55], v[210:213], v[234:237], v[52:55]
	v_mfma_f32_16x16x32_bf16 v[48:51], v[214:217], v[234:237], v[48:51]
	v_mfma_f32_16x16x32_bf16 v[32:35], v[210:213], v[238:241], v[32:35]
	ds_read_b128 v[80:83], v209
	ds_read_b128 v[210:213], v209 offset:64
	ds_read_b128 v[84:87], v202 offset:36928
	v_mfma_f32_16x16x32_bf16 v[76:79], v[214:217], v[238:241], v[44:47]
	ds_read_b128 v[92:95], v209 offset:2304
	ds_read_b128 v[214:217], v209 offset:2368
	v_mfma_f32_16x16x32_bf16 v[120:123], v[192:195], v[218:221], v[120:123]
	ds_read_b128 v[100:103], v209 offset:4608
	ds_read_b128 v[218:221], v209 offset:4672
	s_waitcnt lgkmcnt(3)
	v_mfma_f32_16x16x32_bf16 v[96:99], v[92:95], v[72:75], v[152:155]
	s_nop 2
	ds_read_b128 v[152:155], v209 offset:6912
	ds_read_b128 v[44:47], v209 offset:6976
	v_mfma_f32_16x16x32_bf16 v[104:107], v[192:195], v[222:225], v[104:107]
	v_mfma_f32_16x16x32_bf16 v[12:15], v[192:195], v[226:229], v[88:91]
	v_mfma_f32_16x16x32_bf16 v[88:91], v[80:83], v[72:75], v[156:159]
	s_waitcnt lgkmcnt(3)
	v_mfma_f32_16x16x32_bf16 v[148:151], v[100:103], v[72:75], v[148:151]
	s_waitcnt lgkmcnt(1)
	v_mfma_f32_16x16x32_bf16 v[72:75], v[152:155], v[72:75], v[144:147]
	s_nop 2
	ds_read_b128 v[144:147], v202 offset:39168
	ds_read_b128 v[222:225], v202 offset:39232
	s_waitcnt lgkmcnt(1)
	v_mfma_f32_16x16x32_bf16 v[140:143], v[80:83], v[144:147], v[140:143]
	v_mfma_f32_16x16x32_bf16 v[136:139], v[92:95], v[144:147], v[136:139]
	v_mfma_f32_16x16x32_bf16 v[132:135], v[100:103], v[144:147], v[132:135]
	v_mfma_f32_16x16x32_bf16 v[128:131], v[152:155], v[144:147], v[128:131]
	ds_read_b128 v[144:147], v202 offset:41472
	ds_read_b128 v[226:229], v202 offset:41536
	s_waitcnt lgkmcnt(1)
	v_mfma_f32_16x16x32_bf16 v[124:127], v[80:83], v[144:147], v[124:127]
	v_mfma_f32_16x16x32_bf16 v[120:123], v[92:95], v[144:147], v[120:123]
	v_mfma_f32_16x16x32_bf16 v[116:119], v[100:103], v[144:147], v[116:119]
	v_mfma_f32_16x16x32_bf16 v[112:115], v[152:155], v[144:147], v[112:115]
	ds_read_b128 v[144:147], v202 offset:43776
	ds_read_b128 v[230:233], v202 offset:43840
	v_mfma_f32_16x16x32_bf16 v[56:59], v[192:195], v[234:237], v[56:59]
	s_waitcnt lgkmcnt(1)
	v_mfma_f32_16x16x32_bf16 v[108:111], v[80:83], v[144:147], v[108:111]
	v_mfma_f32_16x16x32_bf16 v[104:107], v[92:95], v[144:147], v[104:107]
	v_mfma_f32_16x16x32_bf16 v[4:7], v[100:103], v[144:147], v[4:7]
	v_mfma_f32_16x16x32_bf16 v[8:11], v[152:155], v[144:147], v[8:11]
	ds_read_b128 v[144:147], v202 offset:46080
	ds_read_b128 v[234:237], v202 offset:46144
	v_mfma_f32_16x16x32_bf16 v[36:39], v[192:195], v[238:241], v[36:39]
	s_waitcnt lgkmcnt(1)
	v_mfma_f32_16x16x32_bf16 v[0:3], v[80:83], v[144:147], v[0:3]
	v_mfma_f32_16x16x32_bf16 v[12:15], v[92:95], v[144:147], v[12:15]
	v_mfma_f32_16x16x32_bf16 v[16:19], v[100:103], v[144:147], v[16:19]
	v_mfma_f32_16x16x32_bf16 v[20:23], v[152:155], v[144:147], v[20:23]
	ds_read_b128 v[144:147], v202 offset:48384
	ds_read_b128 v[238:241], v202 offset:48448
	s_waitcnt lgkmcnt(1)
	v_mfma_f32_16x16x32_bf16 v[24:27], v[80:83], v[144:147], v[24:27]
	v_mfma_f32_16x16x32_bf16 v[28:31], v[92:95], v[144:147], v[28:31]
	v_mfma_f32_16x16x32_bf16 v[68:71], v[100:103], v[144:147], v[68:71]
	v_mfma_f32_16x16x32_bf16 v[64:67], v[152:155], v[144:147], v[64:67]
	ds_read_b128 v[144:147], v202 offset:50688
	ds_read_b128 v[242:245], v202 offset:50752
	s_waitcnt lgkmcnt(1)
	v_mfma_f32_16x16x32_bf16 v[60:63], v[80:83], v[144:147], v[60:63]
	v_mfma_f32_16x16x32_bf16 v[56:59], v[92:95], v[144:147], v[56:59]
	v_mfma_f32_16x16x32_bf16 v[52:55], v[100:103], v[144:147], v[52:55]
	v_mfma_f32_16x16x32_bf16 v[48:51], v[152:155], v[144:147], v[48:51]
	ds_read_b128 v[144:147], v202 offset:52992
	ds_read_b128 v[192:195], v202 offset:53056
	s_waitcnt lgkmcnt(1)
	v_mfma_f32_16x16x32_bf16 v[32:35], v[100:103], v[144:147], v[32:35]
	v_mfma_f32_16x16x32_bf16 v[100:103], v[218:221], v[230:233], v[4:7]
	s_nop 2
	v_lshl_add_u64 v[4:5], s[82:83], 0, v[196:197]
	v_mfma_f32_16x16x32_bf16 v[246:249], v[152:155], v[144:147], v[76:79]
	v_lshl_add_u64 v[6:7], s[84:85], 0, v[196:197]
	v_mfma_f32_16x16x32_bf16 v[152:155], v[214:217], v[84:87], v[96:99]
	v_mfma_f32_16x16x32_bf16 v[96:99], v[44:47], v[230:233], v[8:11]
	s_nop 2
	v_add_co_u32_e32 v8, vcc, s57, v4
	v_mfma_f32_16x16x32_bf16 v[156:159], v[210:213], v[84:87], v[88:91]
	s_nop 0
	v_addc_co_u32_e32 v9, vcc, 0, v5, vcc
	v_mfma_f32_16x16x32_bf16 v[88:91], v[214:217], v[234:237], v[12:15]
	s_nop 2
	v_add_co_u32_e32 v12, vcc, s63, v4
	v_mfma_f32_16x16x32_bf16 v[40:43], v[80:83], v[144:147], v[40:43]
	s_nop 0
	v_addc_co_u32_e32 v13, vcc, 0, v5, vcc
	v_mfma_f32_16x16x32_bf16 v[80:83], v[218:221], v[234:237], v[16:19]
	s_nop 2
	v_add_co_u32_e32 v16, vcc, s64, v4
	v_mfma_f32_16x16x32_bf16 v[36:39], v[92:95], v[144:147], v[36:39]
	s_nop 0
	v_addc_co_u32_e32 v17, vcc, 0, v5, vcc
	v_mfma_f32_16x16x32_bf16 v[148:151], v[218:221], v[84:87], v[148:151]
	v_mfma_f32_16x16x32_bf16 v[144:147], v[44:47], v[84:87], v[72:75]
	v_mfma_f32_16x16x32_bf16 v[84:87], v[44:47], v[234:237], v[20:23]
	s_nop 2
	v_add_co_u32_e32 v20, vcc, s57, v6
	v_mfma_f32_16x16x32_bf16 v[76:79], v[210:213], v[238:241], v[24:27]
	s_nop 0
	v_addc_co_u32_e32 v21, vcc, 0, v7, vcc
	s_nop 0
	v_add_co_u32_e32 v24, vcc, s63, v6
	v_mfma_f32_16x16x32_bf16 v[72:75], v[214:217], v[238:241], v[28:31]
	s_nop 0
	v_addc_co_u32_e32 v25, vcc, 0, v7, vcc
	s_nop 0
	v_add_co_u32_e32 v28, vcc, s64, v6
	v_mfma_f32_16x16x32_bf16 v[92:95], v[210:213], v[234:237], v[0:3]
	s_nop 0
	v_addc_co_u32_e32 v29, vcc, 0, v7, vcc
	s_nop 0
	global_load_dwordx4 v[0:3], v[6:7], off
	s_nop 0
	global_load_dwordx4 v[4:7], v[4:5], off
	s_nop 0
	global_load_dwordx4 v[8:11], v[8:9], off
	s_nop 0
	global_load_dwordx4 v[12:15], v[12:13], off
	s_nop 0
	global_load_dwordx4 v[16:19], v[16:17], off
	s_nop 0
	global_load_dwordx4 v[20:23], v[20:21], off
	s_nop 0
	global_load_dwordx4 v[24:27], v[24:25], off
	v_mfma_f32_16x16x32_bf16 v[140:143], v[210:213], v[222:225], v[140:143]
	global_load_dwordx4 v[28:31], v[28:29], off
	s_waitcnt vmcnt(14)
	ds_write_b128 v200, v[160:163]
	ds_write_b128 v207, v[164:167]
	s_waitcnt vmcnt(13)
	ds_write_b128 v200, v[168:171] offset:9216
	s_waitcnt vmcnt(12)
	ds_write_b128 v200, v[172:175] offset:18432
	s_waitcnt vmcnt(11)
	ds_write_b128 v200, v[176:179] offset:27648
	s_waitcnt vmcnt(10)
	ds_write_b128 v207, v[180:183] offset:9216
	s_waitcnt vmcnt(9)
	ds_write_b128 v207, v[184:187] offset:18432
	s_waitcnt vmcnt(8)
	ds_write_b128 v207, v[188:191] offset:27648
	s_waitcnt lgkmcnt(0)
	v_mfma_f32_16x16x32_bf16 v[136:139], v[214:217], v[222:225], v[136:139]
	s_barrier
	v_mfma_f32_16x16x32_bf16 v[132:135], v[218:221], v[222:225], v[132:135]
	v_mfma_f32_16x16x32_bf16 v[128:131], v[44:47], v[222:225], v[128:131]
	v_mfma_f32_16x16x32_bf16 v[124:127], v[210:213], v[226:229], v[124:127]
	v_mfma_f32_16x16x32_bf16 v[120:123], v[214:217], v[226:229], v[120:123]
	v_mfma_f32_16x16x32_bf16 v[116:119], v[218:221], v[226:229], v[116:119]
	v_mfma_f32_16x16x32_bf16 v[112:115], v[44:47], v[226:229], v[112:115]
	v_mfma_f32_16x16x32_bf16 v[108:111], v[210:213], v[230:233], v[108:111]
	v_mfma_f32_16x16x32_bf16 v[104:107], v[214:217], v[230:233], v[104:107]
	v_mfma_f32_16x16x32_bf16 v[68:71], v[218:221], v[238:241], v[68:71]
	v_mfma_f32_16x16x32_bf16 v[64:67], v[44:47], v[238:241], v[64:67]
	v_mfma_f32_16x16x32_bf16 v[60:63], v[210:213], v[242:245], v[60:63]
	v_mfma_f32_16x16x32_bf16 v[56:59], v[214:217], v[242:245], v[56:59]
	v_mfma_f32_16x16x32_bf16 v[52:55], v[218:221], v[242:245], v[52:55]
	v_mfma_f32_16x16x32_bf16 v[48:51], v[44:47], v[242:245], v[48:51]
	v_mfma_f32_16x16x32_bf16 v[40:43], v[210:213], v[192:195], v[40:43]
	v_mfma_f32_16x16x32_bf16 v[36:39], v[214:217], v[192:195], v[36:39]
	v_mfma_f32_16x16x32_bf16 v[32:35], v[218:221], v[192:195], v[32:35]
	v_mfma_f32_16x16x32_bf16 v[44:47], v[44:47], v[192:195], v[246:249]
	s_cbranch_scc0 .LBB0_1020
	s_cmp_eq_u32 s56, 0
	s_mov_b32 s99, 0x28c4000
	s_cselect_b32 s99, s99, 0x38c4000
	s_lshl_b32 s98, s76, 11
	s_lshl_b32 s100, s75, 1
	s_add_u32 s98, s98, s100
	s_add_u32 s98, s98, s99
	s_add_u32 s100, s34, s98
	s_addc_u32 s101, s35, 0
	v_and_b32_e32 v160, 15, v206
	v_and_b32_e32 v161, 0x80, v201
	v_add_u32_e32 v160, v160, v161
	v_lshlrev_b32_e32 v160, 11, v160
	v_and_b32_e32 v161, 0xc0, v206
	v_lshl_add_u32 v160, v161, 1, v160
	v_and_b32_e32 v161, 4, v201
	v_lshl_add_u32 v160, v161, 3, v160
	v_and_b32_e32 v161, 8, v201
	v_lshl_add_u32 v160, v161, 1, v160
	v_cvt_pk_bf16_f32 v156, v156, v157
	v_cvt_pk_bf16_f32 v157, v158, v159
	v_cvt_pk_bf16_f32 v158, v152, v153
	v_cvt_pk_bf16_f32 v159, v154, v155
	v_cvt_pk_bf16_f32 v148, v148, v149
	v_cvt_pk_bf16_f32 v149, v150, v151
	v_cvt_pk_bf16_f32 v150, v144, v145
	v_cvt_pk_bf16_f32 v151, v146, v147
	v_permlane16_swap_b32_e32 v156, v158
	v_permlane16_swap_b32_e32 v157, v159
	v_permlane16_swap_b32_e32 v148, v150
	v_permlane16_swap_b32_e32 v149, v151
	global_store_dwordx4 v160, v[156:159], s[100:101]
	global_store_dwordx4 v160, v[148:151], s[100:101] offset:64
	s_add_u32 s100, s100, 0x8000
	s_addc_u32 s101, s101, 0
	v_cvt_pk_bf16_f32 v140, v140, v141
	v_cvt_pk_bf16_f32 v141, v142, v143
	v_cvt_pk_bf16_f32 v142, v136, v137
	v_cvt_pk_bf16_f32 v143, v138, v139
	v_cvt_pk_bf16_f32 v132, v132, v133
	v_cvt_pk_bf16_f32 v133, v134, v135
	v_cvt_pk_bf16_f32 v134, v128, v129
	v_cvt_pk_bf16_f32 v135, v130, v131
	v_permlane16_swap_b32_e32 v140, v142
	v_permlane16_swap_b32_e32 v141, v143
	v_permlane16_swap_b32_e32 v132, v134
	v_permlane16_swap_b32_e32 v133, v135
	global_store_dwordx4 v160, v[140:143], s[100:101]
	global_store_dwordx4 v160, v[132:135], s[100:101] offset:64
	s_add_u32 s100, s100, 0x8000
	s_addc_u32 s101, s101, 0
	v_cvt_pk_bf16_f32 v124, v124, v125
	v_cvt_pk_bf16_f32 v125, v126, v127
	v_cvt_pk_bf16_f32 v126, v120, v121
	v_cvt_pk_bf16_f32 v127, v122, v123
	v_cvt_pk_bf16_f32 v116, v116, v117
	v_cvt_pk_bf16_f32 v117, v118, v119
	v_cvt_pk_bf16_f32 v118, v112, v113
	v_cvt_pk_bf16_f32 v119, v114, v115
	v_permlane16_swap_b32_e32 v124, v126
	v_permlane16_swap_b32_e32 v125, v127
	v_permlane16_swap_b32_e32 v116, v118
	v_permlane16_swap_b32_e32 v117, v119
	global_store_dwordx4 v160, v[124:127], s[100:101]
	global_store_dwordx4 v160, v[116:119], s[100:101] offset:64
	s_add_u32 s100, s100, 0x8000
	s_addc_u32 s101, s101, 0
	v_cvt_pk_bf16_f32 v108, v108, v109
	v_cvt_pk_bf16_f32 v109, v110, v111
	v_cvt_pk_bf16_f32 v110, v104, v105
	v_cvt_pk_bf16_f32 v111, v106, v107
	v_cvt_pk_bf16_f32 v100, v100, v101
	v_cvt_pk_bf16_f32 v101, v102, v103
	v_cvt_pk_bf16_f32 v102, v96, v97
	v_cvt_pk_bf16_f32 v103, v98, v99
	v_permlane16_swap_b32_e32 v108, v110
	v_permlane16_swap_b32_e32 v109, v111
	v_permlane16_swap_b32_e32 v100, v102
	v_permlane16_swap_b32_e32 v101, v103
	global_store_dwordx4 v160, v[108:111], s[100:101]
	global_store_dwordx4 v160, v[100:103], s[100:101] offset:64
	s_add_u32 s100, s100, 0x8000
	s_addc_u32 s101, s101, 0
	v_cvt_pk_bf16_f32 v92, v92, v93
	v_cvt_pk_bf16_f32 v93, v94, v95
	v_cvt_pk_bf16_f32 v94, v88, v89
	v_cvt_pk_bf16_f32 v95, v90, v91
	v_cvt_pk_bf16_f32 v80, v80, v81
	v_cvt_pk_bf16_f32 v81, v82, v83
	v_cvt_pk_bf16_f32 v82, v84, v85
	v_cvt_pk_bf16_f32 v83, v86, v87
	v_permlane16_swap_b32_e32 v92, v94
	v_permlane16_swap_b32_e32 v93, v95
	v_permlane16_swap_b32_e32 v80, v82
	v_permlane16_swap_b32_e32 v81, v83
	global_store_dwordx4 v160, v[92:95], s[100:101]
	global_store_dwordx4 v160, v[80:83], s[100:101] offset:64
	s_add_u32 s100, s100, 0x8000
	s_addc_u32 s101, s101, 0
	v_cvt_pk_bf16_f32 v76, v76, v77
	v_cvt_pk_bf16_f32 v77, v78, v79
	v_cvt_pk_bf16_f32 v78, v72, v73
	v_cvt_pk_bf16_f32 v79, v74, v75
	v_cvt_pk_bf16_f32 v68, v68, v69
	v_cvt_pk_bf16_f32 v69, v70, v71
	v_cvt_pk_bf16_f32 v70, v64, v65
	v_cvt_pk_bf16_f32 v71, v66, v67
	v_permlane16_swap_b32_e32 v76, v78
	v_permlane16_swap_b32_e32 v77, v79
	v_permlane16_swap_b32_e32 v68, v70
	v_permlane16_swap_b32_e32 v69, v71
	global_store_dwordx4 v160, v[76:79], s[100:101]
	global_store_dwordx4 v160, v[68:71], s[100:101] offset:64
	s_add_u32 s100, s100, 0x8000
	s_addc_u32 s101, s101, 0
	v_cvt_pk_bf16_f32 v60, v60, v61
	v_cvt_pk_bf16_f32 v61, v62, v63
	v_cvt_pk_bf16_f32 v62, v56, v57
	v_cvt_pk_bf16_f32 v63, v58, v59
	v_cvt_pk_bf16_f32 v52, v52, v53
	v_cvt_pk_bf16_f32 v53, v54, v55
	v_cvt_pk_bf16_f32 v54, v48, v49
	v_cvt_pk_bf16_f32 v55, v50, v51
	v_permlane16_swap_b32_e32 v60, v62
	v_permlane16_swap_b32_e32 v61, v63
	v_permlane16_swap_b32_e32 v52, v54
	v_permlane16_swap_b32_e32 v53, v55
	global_store_dwordx4 v160, v[60:63], s[100:101]
	global_store_dwordx4 v160, v[52:55], s[100:101] offset:64
	s_add_u32 s100, s100, 0x8000
	s_addc_u32 s101, s101, 0
	v_cvt_pk_bf16_f32 v40, v40, v41
	v_cvt_pk_bf16_f32 v41, v42, v43
	v_cvt_pk_bf16_f32 v42, v36, v37
	v_cvt_pk_bf16_f32 v43, v38, v39
	v_cvt_pk_bf16_f32 v32, v32, v33
	v_cvt_pk_bf16_f32 v33, v34, v35
	v_cvt_pk_bf16_f32 v34, v44, v45
	v_cvt_pk_bf16_f32 v35, v46, v47
	v_permlane16_swap_b32_e32 v40, v42
	v_permlane16_swap_b32_e32 v41, v43
	v_permlane16_swap_b32_e32 v32, v34
	v_permlane16_swap_b32_e32 v33, v35
	global_store_dwordx4 v160, v[40:43], s[100:101]
	global_store_dwordx4 v160, v[32:35], s[100:101] offset:64
	s_and_b64 vcc, exec, s[50:51]
	s_mov_b32 s56, s48
	s_mov_b32 s75, s74
	s_mov_b32 s76, s73
	s_mov_b64 s[60:61], s[44:45]
	s_mov_b64 s[58:59], s[42:43]
	s_cbranch_vccz .LBB0_1017
	s_load_dwordx16 s[36:51], s[0:1], 0xc0

.LBB0_1208:
	ds_read_b128 v[160:163], v200
	ds_read_b128 v[164:167], v201
	ds_read_b128 v[180:183], v201 offset:64
	ds_read_b128 v[168:171], v200 offset:64
	ds_read_b128 v[172:175], v201 offset:2304
	ds_read_b128 v[192:195], v201 offset:2368
	ds_read_b128 v[176:179], v201 offset:4608
	ds_read_b128 v[210:213], v201 offset:4672
	ds_read_b128 v[184:187], v201 offset:6912
	ds_read_b128 v[214:217], v201 offset:6976
	s_waitcnt lgkmcnt(8)
	v_mfma_f32_16x16x32_bf16 v[156:159], v[164:167], v[160:163], v[156:159]
	s_add_i32 s80, s79, 2
	s_add_u32 s81, s52, 0xffffff80
	s_addc_u32 s83, s53, -1
	s_waitcnt lgkmcnt(5)
	v_mfma_f32_16x16x32_bf16 v[152:155], v[172:175], v[160:163], v[152:155]
	s_add_u32 s84, s54, 0xffffff80
	s_addc_u32 s85, s55, -1
	s_cmp_lt_u32 s79, 20
	s_waitcnt lgkmcnt(3)
	v_mfma_f32_16x16x32_bf16 v[148:151], v[176:179], v[160:163], v[148:151]
	s_cselect_b32 s82, s81, s44
	s_cselect_b32 s83, s83, s45
	s_cselect_b32 s84, s84, s48
	s_waitcnt lgkmcnt(1)
	v_mfma_f32_16x16x32_bf16 v[144:147], v[184:187], v[160:163], v[144:147]
	ds_read_b128 v[160:163], v200 offset:2304
	ds_read_b128 v[188:191], v200 offset:2368
	s_cselect_b32 s85, s85, s49
	s_cmp_lt_u32 s79, 19
	s_waitcnt lgkmcnt(1)
	v_mfma_f32_16x16x32_bf16 v[140:143], v[164:167], v[160:163], v[140:143]
	v_mfma_f32_16x16x32_bf16 v[136:139], v[172:175], v[160:163], v[136:139]
	v_mfma_f32_16x16x32_bf16 v[132:135], v[176:179], v[160:163], v[132:135]
	v_mfma_f32_16x16x32_bf16 v[128:131], v[184:187], v[160:163], v[128:131]
	ds_read_b128 v[160:163], v200 offset:4608
	ds_read_b128 v[218:221], v200 offset:4672
	s_waitcnt lgkmcnt(1)
	v_mfma_f32_16x16x32_bf16 v[124:127], v[164:167], v[160:163], v[124:127]
	v_mfma_f32_16x16x32_bf16 v[120:123], v[172:175], v[160:163], v[120:123]
	v_mfma_f32_16x16x32_bf16 v[116:119], v[176:179], v[160:163], v[116:119]
	v_mfma_f32_16x16x32_bf16 v[112:115], v[184:187], v[160:163], v[112:115]
	ds_read_b128 v[160:163], v200 offset:6912
	ds_read_b128 v[222:225], v200 offset:6976
	s_waitcnt lgkmcnt(1)
	v_mfma_f32_16x16x32_bf16 v[108:111], v[164:167], v[160:163], v[108:111]
	v_mfma_f32_16x16x32_bf16 v[104:107], v[172:175], v[160:163], v[104:107]
	v_mfma_f32_16x16x32_bf16 v[100:103], v[176:179], v[160:163], v[100:103]
	v_mfma_f32_16x16x32_bf16 v[96:99], v[184:187], v[160:163], v[96:99]
	ds_read_b128 v[160:163], v200 offset:9216
	ds_read_b128 v[226:229], v200 offset:9280
	s_waitcnt lgkmcnt(1)
	v_mfma_f32_16x16x32_bf16 v[92:95], v[164:167], v[160:163], v[92:95]
	v_mfma_f32_16x16x32_bf16 v[88:91], v[172:175], v[160:163], v[88:91]
	v_mfma_f32_16x16x32_bf16 v[80:83], v[176:179], v[160:163], v[80:83]
	v_mfma_f32_16x16x32_bf16 v[84:87], v[184:187], v[160:163], v[84:87]
	ds_read_b128 v[160:163], v200 offset:11520
	ds_read_b128 v[230:233], v200 offset:11584
	s_waitcnt lgkmcnt(1)
	v_mfma_f32_16x16x32_bf16 v[76:79], v[164:167], v[160:163], v[76:79]
	v_mfma_f32_16x16x32_bf16 v[72:75], v[172:175], v[160:163], v[72:75]
	v_mfma_f32_16x16x32_bf16 v[68:71], v[176:179], v[160:163], v[68:71]
	v_mfma_f32_16x16x32_bf16 v[64:67], v[184:187], v[160:163], v[64:67]
	ds_read_b128 v[160:163], v200 offset:13824
	ds_read_b128 v[234:237], v200 offset:13888
	s_waitcnt lgkmcnt(1)
	v_mfma_f32_16x16x32_bf16 v[60:63], v[164:167], v[160:163], v[60:63]
	v_mfma_f32_16x16x32_bf16 v[56:59], v[172:175], v[160:163], v[56:59]
	v_mfma_f32_16x16x32_bf16 v[52:55], v[176:179], v[160:163], v[52:55]
	v_mfma_f32_16x16x32_bf16 v[48:51], v[184:187], v[160:163], v[48:51]
	ds_read_b128 v[160:163], v200 offset:16128
	ds_read_b128 v[238:241], v200 offset:16192
	s_waitcnt vmcnt(6)
	ds_write_b128 v202, v[4:7] offset:36864
	s_waitcnt vmcnt(5)
	ds_write_b128 v202, v[8:11] offset:46080
	s_waitcnt vmcnt(4)
	ds_write_b128 v202, v[12:15] offset:55296
	s_waitcnt vmcnt(3)
	ds_write_b128 v202, v[16:19] offset:64512
	v_mfma_f32_16x16x32_bf16 v[16:19], v[210:213], v[226:229], v[80:83]
	s_waitcnt vmcnt(3)
	ds_write_b128 v208, v[0:3]
	s_waitcnt vmcnt(2)
	ds_write_b128 v208, v[20:23] offset:9216
	s_waitcnt vmcnt(1)
	ds_write_b128 v208, v[24:27] offset:18432
	v_lshl_add_u64 v[80:81], s[82:83], 0, v[196:197]
	s_waitcnt vmcnt(0)
	ds_write_b128 v208, v[28:31] offset:27648
	v_mfma_f32_16x16x32_bf16 v[24:27], v[180:183], v[230:233], v[76:79]
	v_lshl_add_u64 v[82:83], s[84:85], 0, v[196:197]
	s_cselect_b32 s82, s52, s75
	s_cselect_b32 s83, s53, s76
	v_add_co_u32_e32 v76, vcc, s57, v80
	v_mfma_f32_16x16x32_bf16 v[28:31], v[192:195], v[230:233], v[72:75]
	s_nop 0
	v_addc_co_u32_e32 v77, vcc, 0, v81, vcc
	s_cselect_b32 s84, s54, s77
	v_add_co_u32_e32 v72, vcc, s58, v80
	s_waitcnt lgkmcnt(9)
	v_mfma_f32_16x16x32_bf16 v[40:43], v[164:167], v[160:163], v[40:43]
	v_addc_co_u32_e32 v73, vcc, 0, v81, vcc
	v_add_co_u32_e32 v74, vcc, s59, v80
	v_mfma_f32_16x16x32_bf16 v[36:39], v[172:175], v[160:163], v[36:39]
	s_nop 0
	v_addc_co_u32_e32 v75, vcc, 0, v81, vcc
	v_add_co_u32_e32 v78, vcc, s57, v82
	v_mfma_f32_16x16x32_bf16 v[32:35], v[176:179], v[160:163], v[32:35]
	s_nop 0
	v_addc_co_u32_e32 v79, vcc, 0, v83, vcc
	global_load_dwordx4 v[164:167], v[82:83], off
	v_mfma_f32_16x16x32_bf16 v[44:47], v[184:187], v[160:163], v[44:47]
	global_load_dwordx4 v[160:163], v[80:81], off
	v_add_co_u32_e32 v80, vcc, s58, v82
	v_mfma_f32_16x16x32_bf16 v[156:159], v[180:183], v[168:171], v[156:159]
	s_nop 0
	v_addc_co_u32_e32 v81, vcc, 0, v83, vcc
	v_add_co_u32_e32 v82, vcc, s59, v82
	v_mfma_f32_16x16x32_bf16 v[152:155], v[192:195], v[168:171], v[152:155]
	s_nop 0
	v_addc_co_u32_e32 v83, vcc, 0, v83, vcc
	s_cselect_b32 s85, s55, s78
	v_mfma_f32_16x16x32_bf16 v[148:151], v[210:213], v[168:171], v[148:151]
	s_add_u32 s54, s54, 0x100
	s_addc_u32 s55, s55, 0
	s_add_u32 s52, s52, 0x100
	v_mfma_f32_16x16x32_bf16 v[144:147], v[214:217], v[168:171], v[144:147]
	global_load_dwordx4 v[168:171], v[76:77], off
	global_load_dwordx4 v[172:175], v[72:73], off
	global_load_dwordx4 v[176:179], v[74:75], off
	s_addc_u32 s53, s53, 0
	s_cmp_gt_u32 s79, 19
	v_mfma_f32_16x16x32_bf16 v[140:143], v[180:183], v[188:191], v[140:143]
	s_mov_b32 s79, s80
	v_mfma_f32_16x16x32_bf16 v[136:139], v[192:195], v[188:191], v[136:139]
	v_mfma_f32_16x16x32_bf16 v[132:135], v[210:213], v[188:191], v[132:135]
	v_mfma_f32_16x16x32_bf16 v[128:131], v[214:217], v[188:191], v[128:131]
	v_mfma_f32_16x16x32_bf16 v[124:127], v[180:183], v[218:221], v[124:127]
	v_mfma_f32_16x16x32_bf16 v[108:111], v[180:183], v[222:225], v[108:111]
	v_mfma_f32_16x16x32_bf16 v[0:3], v[180:183], v[226:229], v[92:95]
	v_mfma_f32_16x16x32_bf16 v[60:63], v[180:183], v[234:237], v[60:63]
	s_waitcnt lgkmcnt(8)
	v_mfma_f32_16x16x32_bf16 v[40:43], v[180:183], v[238:241], v[40:43]
	global_load_dwordx4 v[180:183], v[78:79], off
	global_load_dwordx4 v[184:187], v[80:81], off
	global_load_dwordx4 v[188:191], v[82:83], off
	s_waitcnt lgkmcnt(0)
	s_barrier
	ds_read_b128 v[72:75], v200 offset:36864
	v_mfma_f32_16x16x32_bf16 v[116:119], v[210:213], v[218:221], v[116:119]
	v_mfma_f32_16x16x32_bf16 v[112:115], v[214:217], v[218:221], v[112:115]
	v_mfma_f32_16x16x32_bf16 v[4:7], v[210:213], v[222:225], v[100:103]
	v_mfma_f32_16x16x32_bf16 v[8:11], v[214:217], v[222:225], v[96:99]
	v_mfma_f32_16x16x32_bf16 v[20:23], v[214:217], v[226:229], v[84:87]
	v_mfma_f32_16x16x32_bf16 v[68:71], v[210:213], v[230:233], v[68:71]
	v_mfma_f32_16x16x32_bf16 v[64:67], v[214:217], v[230:233], v[64:67]
	v_mfma_f32_16x16x32_bf16 v[52:55], v[210:213], v[234:237], v[52:55]
	v_mfma_f32_16x16x32_bf16 v[48:51], v[214:217], v[234:237], v[48:51]
	v_mfma_f32_16x16x32_bf16 v[32:35], v[210:213], v[238:241], v[32:35]
	ds_read_b128 v[80:83], v209
	ds_read_b128 v[210:213], v209 offset:64
	ds_read_b128 v[84:87], v200 offset:36928
	v_mfma_f32_16x16x32_bf16 v[76:79], v[214:217], v[238:241], v[44:47]
	ds_read_b128 v[92:95], v209 offset:2304
	ds_read_b128 v[214:217], v209 offset:2368
	v_mfma_f32_16x16x32_bf16 v[120:123], v[192:195], v[218:221], v[120:123]
	ds_read_b128 v[100:103], v209 offset:4608
	ds_read_b128 v[218:221], v209 offset:4672
	s_waitcnt lgkmcnt(3)
	v_mfma_f32_16x16x32_bf16 v[96:99], v[92:95], v[72:75], v[152:155]
	s_nop 2
	ds_read_b128 v[152:155], v209 offset:6912
	ds_read_b128 v[44:47], v209 offset:6976
	v_mfma_f32_16x16x32_bf16 v[104:107], v[192:195], v[222:225], v[104:107]
	v_mfma_f32_16x16x32_bf16 v[12:15], v[192:195], v[226:229], v[88:91]
	v_mfma_f32_16x16x32_bf16 v[88:91], v[80:83], v[72:75], v[156:159]
	s_waitcnt lgkmcnt(3)
	v_mfma_f32_16x16x32_bf16 v[148:151], v[100:103], v[72:75], v[148:151]
	s_waitcnt lgkmcnt(1)
	v_mfma_f32_16x16x32_bf16 v[72:75], v[152:155], v[72:75], v[144:147]
	s_nop 2
	ds_read_b128 v[144:147], v200 offset:39168
	ds_read_b128 v[222:225], v200 offset:39232
	s_waitcnt lgkmcnt(1)
	v_mfma_f32_16x16x32_bf16 v[140:143], v[80:83], v[144:147], v[140:143]
	v_mfma_f32_16x16x32_bf16 v[136:139], v[92:95], v[144:147], v[136:139]
	v_mfma_f32_16x16x32_bf16 v[132:135], v[100:103], v[144:147], v[132:135]
	v_mfma_f32_16x16x32_bf16 v[128:131], v[152:155], v[144:147], v[128:131]
	ds_read_b128 v[144:147], v200 offset:41472
	ds_read_b128 v[226:229], v200 offset:41536
	s_waitcnt lgkmcnt(1)
	v_mfma_f32_16x16x32_bf16 v[124:127], v[80:83], v[144:147], v[124:127]
	v_mfma_f32_16x16x32_bf16 v[120:123], v[92:95], v[144:147], v[120:123]
	v_mfma_f32_16x16x32_bf16 v[116:119], v[100:103], v[144:147], v[116:119]
	v_mfma_f32_16x16x32_bf16 v[112:115], v[152:155], v[144:147], v[112:115]
	ds_read_b128 v[144:147], v200 offset:43776
	ds_read_b128 v[230:233], v200 offset:43840
	v_mfma_f32_16x16x32_bf16 v[56:59], v[192:195], v[234:237], v[56:59]
	s_waitcnt lgkmcnt(1)
	v_mfma_f32_16x16x32_bf16 v[108:111], v[80:83], v[144:147], v[108:111]
	v_mfma_f32_16x16x32_bf16 v[104:107], v[92:95], v[144:147], v[104:107]
	v_mfma_f32_16x16x32_bf16 v[4:7], v[100:103], v[144:147], v[4:7]
	v_mfma_f32_16x16x32_bf16 v[8:11], v[152:155], v[144:147], v[8:11]
	ds_read_b128 v[144:147], v200 offset:46080
	ds_read_b128 v[234:237], v200 offset:46144
	v_mfma_f32_16x16x32_bf16 v[36:39], v[192:195], v[238:241], v[36:39]
	s_waitcnt lgkmcnt(1)
	v_mfma_f32_16x16x32_bf16 v[0:3], v[80:83], v[144:147], v[0:3]
	v_mfma_f32_16x16x32_bf16 v[12:15], v[92:95], v[144:147], v[12:15]
	v_mfma_f32_16x16x32_bf16 v[16:19], v[100:103], v[144:147], v[16:19]
	v_mfma_f32_16x16x32_bf16 v[20:23], v[152:155], v[144:147], v[20:23]
	ds_read_b128 v[144:147], v200 offset:48384
	ds_read_b128 v[238:241], v200 offset:48448
	s_waitcnt lgkmcnt(1)
	v_mfma_f32_16x16x32_bf16 v[24:27], v[80:83], v[144:147], v[24:27]
	v_mfma_f32_16x16x32_bf16 v[28:31], v[92:95], v[144:147], v[28:31]
	v_mfma_f32_16x16x32_bf16 v[68:71], v[100:103], v[144:147], v[68:71]
	v_mfma_f32_16x16x32_bf16 v[64:67], v[152:155], v[144:147], v[64:67]
	ds_read_b128 v[144:147], v200 offset:50688
	ds_read_b128 v[242:245], v200 offset:50752
	s_waitcnt lgkmcnt(1)
	v_mfma_f32_16x16x32_bf16 v[60:63], v[80:83], v[144:147], v[60:63]
	v_mfma_f32_16x16x32_bf16 v[56:59], v[92:95], v[144:147], v[56:59]
	v_mfma_f32_16x16x32_bf16 v[52:55], v[100:103], v[144:147], v[52:55]
	v_mfma_f32_16x16x32_bf16 v[48:51], v[152:155], v[144:147], v[48:51]
	ds_read_b128 v[144:147], v200 offset:52992
	ds_read_b128 v[192:195], v200 offset:53056
	s_waitcnt lgkmcnt(1)
	v_mfma_f32_16x16x32_bf16 v[32:35], v[100:103], v[144:147], v[32:35]
	v_mfma_f32_16x16x32_bf16 v[100:103], v[218:221], v[230:233], v[4:7]
	s_nop 2
	v_lshl_add_u64 v[4:5], s[82:83], 0, v[196:197]
	v_mfma_f32_16x16x32_bf16 v[246:249], v[152:155], v[144:147], v[76:79]
	v_lshl_add_u64 v[6:7], s[84:85], 0, v[196:197]
	v_mfma_f32_16x16x32_bf16 v[152:155], v[214:217], v[84:87], v[96:99]
	v_mfma_f32_16x16x32_bf16 v[96:99], v[44:47], v[230:233], v[8:11]
	s_nop 2
	v_add_co_u32_e32 v8, vcc, s57, v4
	v_mfma_f32_16x16x32_bf16 v[156:159], v[210:213], v[84:87], v[88:91]
	s_nop 0
	v_addc_co_u32_e32 v9, vcc, 0, v5, vcc
	v_mfma_f32_16x16x32_bf16 v[88:91], v[214:217], v[234:237], v[12:15]
	s_nop 2
	v_add_co_u32_e32 v12, vcc, s58, v4
	v_mfma_f32_16x16x32_bf16 v[40:43], v[80:83], v[144:147], v[40:43]
	s_nop 0
	v_addc_co_u32_e32 v13, vcc, 0, v5, vcc
	v_mfma_f32_16x16x32_bf16 v[80:83], v[218:221], v[234:237], v[16:19]
	s_nop 2
	v_add_co_u32_e32 v16, vcc, s59, v4
	v_mfma_f32_16x16x32_bf16 v[36:39], v[92:95], v[144:147], v[36:39]
	s_nop 0
	v_addc_co_u32_e32 v17, vcc, 0, v5, vcc
	v_mfma_f32_16x16x32_bf16 v[148:151], v[218:221], v[84:87], v[148:151]
	v_mfma_f32_16x16x32_bf16 v[144:147], v[44:47], v[84:87], v[72:75]
	v_mfma_f32_16x16x32_bf16 v[84:87], v[44:47], v[234:237], v[20:23]
	s_nop 2
	v_add_co_u32_e32 v20, vcc, s57, v6
	v_mfma_f32_16x16x32_bf16 v[76:79], v[210:213], v[238:241], v[24:27]
	s_nop 0
	v_addc_co_u32_e32 v21, vcc, 0, v7, vcc
	s_nop 0
	v_add_co_u32_e32 v24, vcc, s58, v6
	v_mfma_f32_16x16x32_bf16 v[72:75], v[214:217], v[238:241], v[28:31]
	s_nop 0
	v_addc_co_u32_e32 v25, vcc, 0, v7, vcc
	s_nop 0
	v_add_co_u32_e32 v28, vcc, s59, v6
	v_mfma_f32_16x16x32_bf16 v[92:95], v[210:213], v[234:237], v[0:3]
	s_nop 0
	v_addc_co_u32_e32 v29, vcc, 0, v7, vcc
	s_nop 0
	global_load_dwordx4 v[0:3], v[6:7], off
	s_nop 0
	global_load_dwordx4 v[4:7], v[4:5], off
	s_nop 0
	global_load_dwordx4 v[8:11], v[8:9], off
	s_nop 0
	global_load_dwordx4 v[12:15], v[12:13], off
	s_nop 0
	global_load_dwordx4 v[16:19], v[16:17], off
	s_nop 0
	global_load_dwordx4 v[20:23], v[20:21], off
	s_nop 0
	global_load_dwordx4 v[24:27], v[24:25], off
	v_mfma_f32_16x16x32_bf16 v[140:143], v[210:213], v[222:225], v[140:143]
	global_load_dwordx4 v[28:31], v[28:29], off
	s_waitcnt vmcnt(14)
	ds_write_b128 v202, v[160:163]
	ds_write_b128 v206, v[164:167]
	s_waitcnt vmcnt(13)
	ds_write_b128 v202, v[168:171] offset:9216
	s_waitcnt vmcnt(12)
	ds_write_b128 v202, v[172:175] offset:18432
	s_waitcnt vmcnt(11)
	ds_write_b128 v202, v[176:179] offset:27648
	s_waitcnt vmcnt(10)
	ds_write_b128 v206, v[180:183] offset:9216
	s_waitcnt vmcnt(9)
	ds_write_b128 v206, v[184:187] offset:18432
	s_waitcnt vmcnt(8)
	ds_write_b128 v206, v[188:191] offset:27648
	s_waitcnt lgkmcnt(0)
	v_mfma_f32_16x16x32_bf16 v[136:139], v[214:217], v[222:225], v[136:139]
	s_barrier
	v_mfma_f32_16x16x32_bf16 v[132:135], v[218:221], v[222:225], v[132:135]
	v_mfma_f32_16x16x32_bf16 v[128:131], v[44:47], v[222:225], v[128:131]
	v_mfma_f32_16x16x32_bf16 v[124:127], v[210:213], v[226:229], v[124:127]
	v_mfma_f32_16x16x32_bf16 v[120:123], v[214:217], v[226:229], v[120:123]
	v_mfma_f32_16x16x32_bf16 v[116:119], v[218:221], v[226:229], v[116:119]
	v_mfma_f32_16x16x32_bf16 v[112:115], v[44:47], v[226:229], v[112:115]
	v_mfma_f32_16x16x32_bf16 v[108:111], v[210:213], v[230:233], v[108:111]
	v_mfma_f32_16x16x32_bf16 v[104:107], v[214:217], v[230:233], v[104:107]
	v_mfma_f32_16x16x32_bf16 v[68:71], v[218:221], v[238:241], v[68:71]
	v_mfma_f32_16x16x32_bf16 v[64:67], v[44:47], v[238:241], v[64:67]
	v_mfma_f32_16x16x32_bf16 v[60:63], v[210:213], v[242:245], v[60:63]
	v_mfma_f32_16x16x32_bf16 v[56:59], v[214:217], v[242:245], v[56:59]
	v_mfma_f32_16x16x32_bf16 v[52:55], v[218:221], v[242:245], v[52:55]
	v_mfma_f32_16x16x32_bf16 v[48:51], v[44:47], v[242:245], v[48:51]
	v_mfma_f32_16x16x32_bf16 v[40:43], v[210:213], v[192:195], v[40:43]
	v_mfma_f32_16x16x32_bf16 v[36:39], v[214:217], v[192:195], v[36:39]
	v_mfma_f32_16x16x32_bf16 v[32:35], v[218:221], v[192:195], v[32:35]
	v_mfma_f32_16x16x32_bf16 v[44:47], v[44:47], v[192:195], v[246:249]
	s_cbranch_scc0 .LBB0_1208
	s_cmp_eq_u32 s72, 0
	s_mov_b32 s99, 0x6a44000
	s_cselect_b32 s99, s99, 0x7a44000
	s_lshl_b32 s98, s74, 11
	s_lshl_b32 s100, s73, 1
	s_add_u32 s98, s98, s100
	s_add_u32 s98, s98, s99
	s_add_u32 s100, s34, s98
	s_addc_u32 s101, s35, 0
	v_and_b32_e32 v160, 15, v207
	v_and_b32_e32 v161, 0x80, v203
	v_add_u32_e32 v160, v160, v161
	v_lshlrev_b32_e32 v160, 11, v160
	v_and_b32_e32 v161, 0xc0, v207
	v_lshl_add_u32 v160, v161, 1, v160
	v_and_b32_e32 v161, 4, v203
	v_lshl_add_u32 v160, v161, 3, v160
	v_and_b32_e32 v161, 8, v203
	v_lshl_add_u32 v160, v161, 1, v160
	v_cvt_pk_bf16_f32 v156, v156, v157
	v_cvt_pk_bf16_f32 v157, v158, v159
	v_cvt_pk_bf16_f32 v158, v152, v153
	v_cvt_pk_bf16_f32 v159, v154, v155
	v_cvt_pk_bf16_f32 v148, v148, v149
	v_cvt_pk_bf16_f32 v149, v150, v151
	v_cvt_pk_bf16_f32 v150, v144, v145
	v_cvt_pk_bf16_f32 v151, v146, v147
	v_permlane16_swap_b32_e32 v156, v158
	v_permlane16_swap_b32_e32 v157, v159
	v_permlane16_swap_b32_e32 v148, v150
	v_permlane16_swap_b32_e32 v149, v151
	global_store_dwordx4 v160, v[156:159], s[100:101]
	global_store_dwordx4 v160, v[148:151], s[100:101] offset:64
	s_add_u32 s100, s100, 0x8000
	s_addc_u32 s101, s101, 0
	v_cvt_pk_bf16_f32 v140, v140, v141
	v_cvt_pk_bf16_f32 v141, v142, v143
	v_cvt_pk_bf16_f32 v142, v136, v137
	v_cvt_pk_bf16_f32 v143, v138, v139
	v_cvt_pk_bf16_f32 v132, v132, v133
	v_cvt_pk_bf16_f32 v133, v134, v135
	v_cvt_pk_bf16_f32 v134, v128, v129
	v_cvt_pk_bf16_f32 v135, v130, v131
	v_permlane16_swap_b32_e32 v140, v142
	v_permlane16_swap_b32_e32 v141, v143
	v_permlane16_swap_b32_e32 v132, v134
	v_permlane16_swap_b32_e32 v133, v135
	global_store_dwordx4 v160, v[140:143], s[100:101]
	global_store_dwordx4 v160, v[132:135], s[100:101] offset:64
	s_add_u32 s100, s100, 0x8000
	s_addc_u32 s101, s101, 0
	v_cvt_pk_bf16_f32 v124, v124, v125
	v_cvt_pk_bf16_f32 v125, v126, v127
	v_cvt_pk_bf16_f32 v126, v120, v121
	v_cvt_pk_bf16_f32 v127, v122, v123
	v_cvt_pk_bf16_f32 v116, v116, v117
	v_cvt_pk_bf16_f32 v117, v118, v119
	v_cvt_pk_bf16_f32 v118, v112, v113
	v_cvt_pk_bf16_f32 v119, v114, v115
	v_permlane16_swap_b32_e32 v124, v126
	v_permlane16_swap_b32_e32 v125, v127
	v_permlane16_swap_b32_e32 v116, v118
	v_permlane16_swap_b32_e32 v117, v119
	global_store_dwordx4 v160, v[124:127], s[100:101]
	global_store_dwordx4 v160, v[116:119], s[100:101] offset:64
	s_add_u32 s100, s100, 0x8000
	s_addc_u32 s101, s101, 0
	v_cvt_pk_bf16_f32 v108, v108, v109
	v_cvt_pk_bf16_f32 v109, v110, v111
	v_cvt_pk_bf16_f32 v110, v104, v105
	v_cvt_pk_bf16_f32 v111, v106, v107
	v_cvt_pk_bf16_f32 v100, v100, v101
	v_cvt_pk_bf16_f32 v101, v102, v103
	v_cvt_pk_bf16_f32 v102, v96, v97
	v_cvt_pk_bf16_f32 v103, v98, v99
	v_permlane16_swap_b32_e32 v108, v110
	v_permlane16_swap_b32_e32 v109, v111
	v_permlane16_swap_b32_e32 v100, v102
	v_permlane16_swap_b32_e32 v101, v103
	global_store_dwordx4 v160, v[108:111], s[100:101]
	global_store_dwordx4 v160, v[100:103], s[100:101] offset:64
	s_add_u32 s100, s100, 0x8000
	s_addc_u32 s101, s101, 0
	v_cvt_pk_bf16_f32 v92, v92, v93
	v_cvt_pk_bf16_f32 v93, v94, v95
	v_cvt_pk_bf16_f32 v94, v88, v89
	v_cvt_pk_bf16_f32 v95, v90, v91
	v_cvt_pk_bf16_f32 v80, v80, v81
	v_cvt_pk_bf16_f32 v81, v82, v83
	v_cvt_pk_bf16_f32 v82, v84, v85
	v_cvt_pk_bf16_f32 v83, v86, v87
	v_permlane16_swap_b32_e32 v92, v94
	v_permlane16_swap_b32_e32 v93, v95
	v_permlane16_swap_b32_e32 v80, v82
	v_permlane16_swap_b32_e32 v81, v83
	global_store_dwordx4 v160, v[92:95], s[100:101]
	global_store_dwordx4 v160, v[80:83], s[100:101] offset:64
	s_add_u32 s100, s100, 0x8000
	s_addc_u32 s101, s101, 0
	v_cvt_pk_bf16_f32 v76, v76, v77
	v_cvt_pk_bf16_f32 v77, v78, v79
	v_cvt_pk_bf16_f32 v78, v72, v73
	v_cvt_pk_bf16_f32 v79, v74, v75
	v_cvt_pk_bf16_f32 v68, v68, v69
	v_cvt_pk_bf16_f32 v69, v70, v71
	v_cvt_pk_bf16_f32 v70, v64, v65
	v_cvt_pk_bf16_f32 v71, v66, v67
	v_permlane16_swap_b32_e32 v76, v78
	v_permlane16_swap_b32_e32 v77, v79
	v_permlane16_swap_b32_e32 v68, v70
	v_permlane16_swap_b32_e32 v69, v71
	global_store_dwordx4 v160, v[76:79], s[100:101]
	global_store_dwordx4 v160, v[68:71], s[100:101] offset:64
	s_add_u32 s100, s100, 0x8000
	s_addc_u32 s101, s101, 0
	v_cvt_pk_bf16_f32 v60, v60, v61
	v_cvt_pk_bf16_f32 v61, v62, v63
	v_cvt_pk_bf16_f32 v62, v56, v57
	v_cvt_pk_bf16_f32 v63, v58, v59
	v_cvt_pk_bf16_f32 v52, v52, v53
	v_cvt_pk_bf16_f32 v53, v54, v55
	v_cvt_pk_bf16_f32 v54, v48, v49
	v_cvt_pk_bf16_f32 v55, v50, v51
	v_permlane16_swap_b32_e32 v60, v62
	v_permlane16_swap_b32_e32 v61, v63
	v_permlane16_swap_b32_e32 v52, v54
	v_permlane16_swap_b32_e32 v53, v55
	global_store_dwordx4 v160, v[60:63], s[100:101]
	global_store_dwordx4 v160, v[52:55], s[100:101] offset:64
	s_add_u32 s100, s100, 0x8000
	s_addc_u32 s101, s101, 0
	v_cvt_pk_bf16_f32 v40, v40, v41
	v_cvt_pk_bf16_f32 v41, v42, v43
	v_cvt_pk_bf16_f32 v42, v36, v37
	v_cvt_pk_bf16_f32 v43, v38, v39
	v_cvt_pk_bf16_f32 v32, v32, v33
	v_cvt_pk_bf16_f32 v33, v34, v35
	v_cvt_pk_bf16_f32 v34, v44, v45
	v_cvt_pk_bf16_f32 v35, v46, v47
	v_permlane16_swap_b32_e32 v40, v42
	v_permlane16_swap_b32_e32 v41, v43
	v_permlane16_swap_b32_e32 v32, v34
	v_permlane16_swap_b32_e32 v33, v35
	global_store_dwordx4 v160, v[40:43], s[100:101]
	global_store_dwordx4 v160, v[32:35], s[100:101] offset:64
	s_and_b64 vcc, exec, s[50:51]
	s_mov_b32 s72, s71
	s_mov_b32 s73, s70
	s_mov_b32 s74, s69
	s_mov_b64 s[54:55], s[48:49]
	s_mov_b64 s[52:53], s[44:45]
	s_cbranch_vccz .LBB0_1205
	s_load_dwordx16 s[36:51], s[0:1], 0xc0

.LBB0_1511:
	ds_read_b128 v[160:163], v200
	ds_read_b128 v[164:167], v201
	ds_read_b128 v[180:183], v201 offset:64
	ds_read_b128 v[168:171], v200 offset:64
	ds_read_b128 v[172:175], v201 offset:2304
	ds_read_b128 v[192:195], v201 offset:2368
	ds_read_b128 v[176:179], v201 offset:4608
	ds_read_b128 v[210:213], v201 offset:4672
	ds_read_b128 v[184:187], v201 offset:6912
	ds_read_b128 v[214:217], v201 offset:6976
	s_waitcnt lgkmcnt(8)
	v_mfma_f32_16x16x32_bf16 v[156:159], v[164:167], v[160:163], v[156:159]
	s_add_i32 s86, s85, 2
	s_add_u32 s87, s56, 0xffffff80
	s_addc_u32 s93, s57, -1
	s_waitcnt lgkmcnt(5)
	v_mfma_f32_16x16x32_bf16 v[152:155], v[172:175], v[160:163], v[152:155]
	s_add_u32 s94, s58, 0xffffff80
	s_addc_u32 s95, s59, -1
	s_cmp_lt_u32 s85, 20
	s_waitcnt lgkmcnt(3)
	v_mfma_f32_16x16x32_bf16 v[148:151], v[176:179], v[160:163], v[148:151]
	s_cselect_b32 s92, s87, s50
	s_cselect_b32 s93, s93, s51
	s_cselect_b32 s94, s94, s52
	s_waitcnt lgkmcnt(1)
	v_mfma_f32_16x16x32_bf16 v[144:147], v[184:187], v[160:163], v[144:147]
	ds_read_b128 v[160:163], v200 offset:2304
	ds_read_b128 v[188:191], v200 offset:2368
	s_cselect_b32 s95, s95, s53
	s_cmp_lt_u32 s85, 19
	s_waitcnt lgkmcnt(1)
	v_mfma_f32_16x16x32_bf16 v[140:143], v[164:167], v[160:163], v[140:143]
	v_mfma_f32_16x16x32_bf16 v[136:139], v[172:175], v[160:163], v[136:139]
	v_mfma_f32_16x16x32_bf16 v[132:135], v[176:179], v[160:163], v[132:135]
	v_mfma_f32_16x16x32_bf16 v[128:131], v[184:187], v[160:163], v[128:131]
	ds_read_b128 v[160:163], v200 offset:4608
	ds_read_b128 v[218:221], v200 offset:4672
	s_waitcnt lgkmcnt(1)
	v_mfma_f32_16x16x32_bf16 v[124:127], v[164:167], v[160:163], v[124:127]
	v_mfma_f32_16x16x32_bf16 v[120:123], v[172:175], v[160:163], v[120:123]
	v_mfma_f32_16x16x32_bf16 v[116:119], v[176:179], v[160:163], v[116:119]
	v_mfma_f32_16x16x32_bf16 v[112:115], v[184:187], v[160:163], v[112:115]
	ds_read_b128 v[160:163], v200 offset:6912
	ds_read_b128 v[222:225], v200 offset:6976
	s_waitcnt lgkmcnt(1)
	v_mfma_f32_16x16x32_bf16 v[108:111], v[164:167], v[160:163], v[108:111]
	v_mfma_f32_16x16x32_bf16 v[104:107], v[172:175], v[160:163], v[104:107]
	v_mfma_f32_16x16x32_bf16 v[100:103], v[176:179], v[160:163], v[100:103]
	v_mfma_f32_16x16x32_bf16 v[96:99], v[184:187], v[160:163], v[96:99]
	ds_read_b128 v[160:163], v200 offset:9216
	ds_read_b128 v[226:229], v200 offset:9280
	s_waitcnt lgkmcnt(1)
	v_mfma_f32_16x16x32_bf16 v[92:95], v[164:167], v[160:163], v[92:95]
	v_mfma_f32_16x16x32_bf16 v[88:91], v[172:175], v[160:163], v[88:91]
	v_mfma_f32_16x16x32_bf16 v[80:83], v[176:179], v[160:163], v[80:83]
	v_mfma_f32_16x16x32_bf16 v[84:87], v[184:187], v[160:163], v[84:87]
	ds_read_b128 v[160:163], v200 offset:11520
	ds_read_b128 v[230:233], v200 offset:11584
	s_waitcnt lgkmcnt(1)
	v_mfma_f32_16x16x32_bf16 v[76:79], v[164:167], v[160:163], v[76:79]
	v_mfma_f32_16x16x32_bf16 v[72:75], v[172:175], v[160:163], v[72:75]
	v_mfma_f32_16x16x32_bf16 v[68:71], v[176:179], v[160:163], v[68:71]
	v_mfma_f32_16x16x32_bf16 v[64:67], v[184:187], v[160:163], v[64:67]
	ds_read_b128 v[160:163], v200 offset:13824
	ds_read_b128 v[234:237], v200 offset:13888
	s_waitcnt lgkmcnt(1)
	v_mfma_f32_16x16x32_bf16 v[60:63], v[164:167], v[160:163], v[60:63]
	v_mfma_f32_16x16x32_bf16 v[56:59], v[172:175], v[160:163], v[56:59]
	v_mfma_f32_16x16x32_bf16 v[52:55], v[176:179], v[160:163], v[52:55]
	v_mfma_f32_16x16x32_bf16 v[48:51], v[184:187], v[160:163], v[48:51]
	ds_read_b128 v[160:163], v200 offset:16128
	ds_read_b128 v[238:241], v200 offset:16192
	s_waitcnt vmcnt(6)
	ds_write_b128 v202, v[4:7] offset:36864
	s_waitcnt vmcnt(5)
	ds_write_b128 v202, v[8:11] offset:46080
	s_waitcnt vmcnt(4)
	ds_write_b128 v202, v[12:15] offset:55296
	s_waitcnt vmcnt(3)
	ds_write_b128 v202, v[16:19] offset:64512
	v_mfma_f32_16x16x32_bf16 v[16:19], v[210:213], v[226:229], v[80:83]
	s_waitcnt vmcnt(3)
	ds_write_b128 v208, v[0:3]
	s_waitcnt vmcnt(2)
	ds_write_b128 v208, v[20:23] offset:9216
	s_waitcnt vmcnt(1)
	ds_write_b128 v208, v[24:27] offset:18432
	v_lshl_add_u64 v[80:81], s[92:93], 0, v[196:197]
	s_waitcnt vmcnt(0)
	ds_write_b128 v208, v[28:31] offset:27648
	v_mfma_f32_16x16x32_bf16 v[24:27], v[180:183], v[230:233], v[76:79]
	v_lshl_add_u64 v[82:83], s[94:95], 0, v[196:197]
	s_cselect_b32 s92, s56, s81
	s_cselect_b32 s93, s57, s82
	v_add_co_u32_e32 v76, vcc, s61, v80
	v_mfma_f32_16x16x32_bf16 v[28:31], v[192:195], v[230:233], v[72:75]
	s_nop 0
	v_addc_co_u32_e32 v77, vcc, 0, v81, vcc
	s_cselect_b32 s94, s58, s83
	v_add_co_u32_e32 v72, vcc, s62, v80
	s_waitcnt lgkmcnt(9)
	v_mfma_f32_16x16x32_bf16 v[40:43], v[164:167], v[160:163], v[40:43]
	v_addc_co_u32_e32 v73, vcc, 0, v81, vcc
	v_add_co_u32_e32 v74, vcc, s63, v80
	v_mfma_f32_16x16x32_bf16 v[36:39], v[172:175], v[160:163], v[36:39]
	s_nop 0
	v_addc_co_u32_e32 v75, vcc, 0, v81, vcc
	v_add_co_u32_e32 v78, vcc, s61, v82
	v_mfma_f32_16x16x32_bf16 v[32:35], v[176:179], v[160:163], v[32:35]
	s_nop 0
	v_addc_co_u32_e32 v79, vcc, 0, v83, vcc
	global_load_dwordx4 v[164:167], v[82:83], off
	v_mfma_f32_16x16x32_bf16 v[44:47], v[184:187], v[160:163], v[44:47]
	global_load_dwordx4 v[160:163], v[80:81], off
	v_add_co_u32_e32 v80, vcc, s62, v82
	v_mfma_f32_16x16x32_bf16 v[156:159], v[180:183], v[168:171], v[156:159]
	s_nop 0
	v_addc_co_u32_e32 v81, vcc, 0, v83, vcc
	v_add_co_u32_e32 v82, vcc, s63, v82
	v_mfma_f32_16x16x32_bf16 v[152:155], v[192:195], v[168:171], v[152:155]
	s_nop 0
	v_addc_co_u32_e32 v83, vcc, 0, v83, vcc
	s_cselect_b32 s95, s59, s84
	v_mfma_f32_16x16x32_bf16 v[148:151], v[210:213], v[168:171], v[148:151]
	s_add_u32 s58, s58, 0x100
	s_addc_u32 s59, s59, 0
	s_add_u32 s56, s56, 0x100
	v_mfma_f32_16x16x32_bf16 v[144:147], v[214:217], v[168:171], v[144:147]
	global_load_dwordx4 v[168:171], v[76:77], off
	global_load_dwordx4 v[172:175], v[72:73], off
	global_load_dwordx4 v[176:179], v[74:75], off
	s_addc_u32 s57, s57, 0
	s_cmp_gt_u32 s85, 19
	v_mfma_f32_16x16x32_bf16 v[140:143], v[180:183], v[188:191], v[140:143]
	s_mov_b32 s85, s86
	v_mfma_f32_16x16x32_bf16 v[136:139], v[192:195], v[188:191], v[136:139]
	v_mfma_f32_16x16x32_bf16 v[132:135], v[210:213], v[188:191], v[132:135]
	v_mfma_f32_16x16x32_bf16 v[128:131], v[214:217], v[188:191], v[128:131]
	v_mfma_f32_16x16x32_bf16 v[124:127], v[180:183], v[218:221], v[124:127]
	v_mfma_f32_16x16x32_bf16 v[108:111], v[180:183], v[222:225], v[108:111]
	v_mfma_f32_16x16x32_bf16 v[0:3], v[180:183], v[226:229], v[92:95]
	v_mfma_f32_16x16x32_bf16 v[60:63], v[180:183], v[234:237], v[60:63]
	s_waitcnt lgkmcnt(8)
	v_mfma_f32_16x16x32_bf16 v[40:43], v[180:183], v[238:241], v[40:43]
	global_load_dwordx4 v[180:183], v[78:79], off
	global_load_dwordx4 v[184:187], v[80:81], off
	global_load_dwordx4 v[188:191], v[82:83], off
	s_waitcnt lgkmcnt(0)
	s_barrier
	ds_read_b128 v[72:75], v200 offset:36864
	v_mfma_f32_16x16x32_bf16 v[116:119], v[210:213], v[218:221], v[116:119]
	v_mfma_f32_16x16x32_bf16 v[112:115], v[214:217], v[218:221], v[112:115]
	v_mfma_f32_16x16x32_bf16 v[4:7], v[210:213], v[222:225], v[100:103]
	v_mfma_f32_16x16x32_bf16 v[8:11], v[214:217], v[222:225], v[96:99]
	v_mfma_f32_16x16x32_bf16 v[20:23], v[214:217], v[226:229], v[84:87]
	v_mfma_f32_16x16x32_bf16 v[68:71], v[210:213], v[230:233], v[68:71]
	v_mfma_f32_16x16x32_bf16 v[64:67], v[214:217], v[230:233], v[64:67]
	v_mfma_f32_16x16x32_bf16 v[52:55], v[210:213], v[234:237], v[52:55]
	v_mfma_f32_16x16x32_bf16 v[48:51], v[214:217], v[234:237], v[48:51]
	v_mfma_f32_16x16x32_bf16 v[32:35], v[210:213], v[238:241], v[32:35]
	ds_read_b128 v[80:83], v209
	ds_read_b128 v[210:213], v209 offset:64
	ds_read_b128 v[84:87], v200 offset:36928
	v_mfma_f32_16x16x32_bf16 v[76:79], v[214:217], v[238:241], v[44:47]
	ds_read_b128 v[92:95], v209 offset:2304
	ds_read_b128 v[214:217], v209 offset:2368
	v_mfma_f32_16x16x32_bf16 v[120:123], v[192:195], v[218:221], v[120:123]
	ds_read_b128 v[100:103], v209 offset:4608
	ds_read_b128 v[218:221], v209 offset:4672
	s_waitcnt lgkmcnt(3)
	v_mfma_f32_16x16x32_bf16 v[96:99], v[92:95], v[72:75], v[152:155]
	s_nop 2
	ds_read_b128 v[152:155], v209 offset:6912
	ds_read_b128 v[44:47], v209 offset:6976
	v_mfma_f32_16x16x32_bf16 v[104:107], v[192:195], v[222:225], v[104:107]
	v_mfma_f32_16x16x32_bf16 v[12:15], v[192:195], v[226:229], v[88:91]
	v_mfma_f32_16x16x32_bf16 v[88:91], v[80:83], v[72:75], v[156:159]
	s_waitcnt lgkmcnt(3)
	v_mfma_f32_16x16x32_bf16 v[148:151], v[100:103], v[72:75], v[148:151]
	s_waitcnt lgkmcnt(1)
	v_mfma_f32_16x16x32_bf16 v[72:75], v[152:155], v[72:75], v[144:147]
	s_nop 2
	ds_read_b128 v[144:147], v200 offset:39168
	ds_read_b128 v[222:225], v200 offset:39232
	s_waitcnt lgkmcnt(1)
	v_mfma_f32_16x16x32_bf16 v[140:143], v[80:83], v[144:147], v[140:143]
	v_mfma_f32_16x16x32_bf16 v[136:139], v[92:95], v[144:147], v[136:139]
	v_mfma_f32_16x16x32_bf16 v[132:135], v[100:103], v[144:147], v[132:135]
	v_mfma_f32_16x16x32_bf16 v[128:131], v[152:155], v[144:147], v[128:131]
	ds_read_b128 v[144:147], v200 offset:41472
	ds_read_b128 v[226:229], v200 offset:41536
	s_waitcnt lgkmcnt(1)
	v_mfma_f32_16x16x32_bf16 v[124:127], v[80:83], v[144:147], v[124:127]
	v_mfma_f32_16x16x32_bf16 v[120:123], v[92:95], v[144:147], v[120:123]
	v_mfma_f32_16x16x32_bf16 v[116:119], v[100:103], v[144:147], v[116:119]
	v_mfma_f32_16x16x32_bf16 v[112:115], v[152:155], v[144:147], v[112:115]
	ds_read_b128 v[144:147], v200 offset:43776
	ds_read_b128 v[230:233], v200 offset:43840
	v_mfma_f32_16x16x32_bf16 v[56:59], v[192:195], v[234:237], v[56:59]
	s_waitcnt lgkmcnt(1)
	v_mfma_f32_16x16x32_bf16 v[108:111], v[80:83], v[144:147], v[108:111]
	v_mfma_f32_16x16x32_bf16 v[104:107], v[92:95], v[144:147], v[104:107]
	v_mfma_f32_16x16x32_bf16 v[4:7], v[100:103], v[144:147], v[4:7]
	v_mfma_f32_16x16x32_bf16 v[8:11], v[152:155], v[144:147], v[8:11]
	ds_read_b128 v[144:147], v200 offset:46080
	ds_read_b128 v[234:237], v200 offset:46144
	v_mfma_f32_16x16x32_bf16 v[36:39], v[192:195], v[238:241], v[36:39]
	s_waitcnt lgkmcnt(1)
	v_mfma_f32_16x16x32_bf16 v[0:3], v[80:83], v[144:147], v[0:3]
	v_mfma_f32_16x16x32_bf16 v[12:15], v[92:95], v[144:147], v[12:15]
	v_mfma_f32_16x16x32_bf16 v[16:19], v[100:103], v[144:147], v[16:19]
	v_mfma_f32_16x16x32_bf16 v[20:23], v[152:155], v[144:147], v[20:23]
	ds_read_b128 v[144:147], v200 offset:48384
	ds_read_b128 v[238:241], v200 offset:48448
	s_waitcnt lgkmcnt(1)
	v_mfma_f32_16x16x32_bf16 v[24:27], v[80:83], v[144:147], v[24:27]
	v_mfma_f32_16x16x32_bf16 v[28:31], v[92:95], v[144:147], v[28:31]
	v_mfma_f32_16x16x32_bf16 v[68:71], v[100:103], v[144:147], v[68:71]
	v_mfma_f32_16x16x32_bf16 v[64:67], v[152:155], v[144:147], v[64:67]
	ds_read_b128 v[144:147], v200 offset:50688
	ds_read_b128 v[242:245], v200 offset:50752
	s_waitcnt lgkmcnt(1)
	v_mfma_f32_16x16x32_bf16 v[60:63], v[80:83], v[144:147], v[60:63]
	v_mfma_f32_16x16x32_bf16 v[56:59], v[92:95], v[144:147], v[56:59]
	v_mfma_f32_16x16x32_bf16 v[52:55], v[100:103], v[144:147], v[52:55]
	v_mfma_f32_16x16x32_bf16 v[48:51], v[152:155], v[144:147], v[48:51]
	ds_read_b128 v[144:147], v200 offset:52992
	ds_read_b128 v[192:195], v200 offset:53056
	s_waitcnt lgkmcnt(1)
	v_mfma_f32_16x16x32_bf16 v[32:35], v[100:103], v[144:147], v[32:35]
	v_mfma_f32_16x16x32_bf16 v[100:103], v[218:221], v[230:233], v[4:7]
	s_nop 2
	v_lshl_add_u64 v[4:5], s[92:93], 0, v[196:197]
	v_mfma_f32_16x16x32_bf16 v[246:249], v[152:155], v[144:147], v[76:79]
	v_lshl_add_u64 v[6:7], s[94:95], 0, v[196:197]
	v_mfma_f32_16x16x32_bf16 v[152:155], v[214:217], v[84:87], v[96:99]
	v_mfma_f32_16x16x32_bf16 v[96:99], v[44:47], v[230:233], v[8:11]
	s_nop 2
	v_add_co_u32_e32 v8, vcc, s61, v4
	v_mfma_f32_16x16x32_bf16 v[156:159], v[210:213], v[84:87], v[88:91]
	s_nop 0
	v_addc_co_u32_e32 v9, vcc, 0, v5, vcc
	v_mfma_f32_16x16x32_bf16 v[88:91], v[214:217], v[234:237], v[12:15]
	s_nop 2
	v_add_co_u32_e32 v12, vcc, s62, v4
	v_mfma_f32_16x16x32_bf16 v[40:43], v[80:83], v[144:147], v[40:43]
	s_nop 0
	v_addc_co_u32_e32 v13, vcc, 0, v5, vcc
	v_mfma_f32_16x16x32_bf16 v[80:83], v[218:221], v[234:237], v[16:19]
	s_nop 2
	v_add_co_u32_e32 v16, vcc, s63, v4
	v_mfma_f32_16x16x32_bf16 v[36:39], v[92:95], v[144:147], v[36:39]
	s_nop 0
	v_addc_co_u32_e32 v17, vcc, 0, v5, vcc
	v_mfma_f32_16x16x32_bf16 v[148:151], v[218:221], v[84:87], v[148:151]
	v_mfma_f32_16x16x32_bf16 v[144:147], v[44:47], v[84:87], v[72:75]
	v_mfma_f32_16x16x32_bf16 v[84:87], v[44:47], v[234:237], v[20:23]
	s_nop 2
	v_add_co_u32_e32 v20, vcc, s61, v6
	v_mfma_f32_16x16x32_bf16 v[76:79], v[210:213], v[238:241], v[24:27]
	s_nop 0
	v_addc_co_u32_e32 v21, vcc, 0, v7, vcc
	s_nop 0
	v_add_co_u32_e32 v24, vcc, s62, v6
	v_mfma_f32_16x16x32_bf16 v[72:75], v[214:217], v[238:241], v[28:31]
	s_nop 0
	v_addc_co_u32_e32 v25, vcc, 0, v7, vcc
	s_nop 0
	v_add_co_u32_e32 v28, vcc, s63, v6
	v_mfma_f32_16x16x32_bf16 v[92:95], v[210:213], v[234:237], v[0:3]
	s_nop 0
	v_addc_co_u32_e32 v29, vcc, 0, v7, vcc
	s_nop 0
	global_load_dwordx4 v[0:3], v[6:7], off
	s_nop 0
	global_load_dwordx4 v[4:7], v[4:5], off
	s_nop 0
	global_load_dwordx4 v[8:11], v[8:9], off
	s_nop 0
	global_load_dwordx4 v[12:15], v[12:13], off
	s_nop 0
	global_load_dwordx4 v[16:19], v[16:17], off
	s_nop 0
	global_load_dwordx4 v[20:23], v[20:21], off
	s_nop 0
	global_load_dwordx4 v[24:27], v[24:25], off
	v_mfma_f32_16x16x32_bf16 v[140:143], v[210:213], v[222:225], v[140:143]
	global_load_dwordx4 v[28:31], v[28:29], off
	s_waitcnt vmcnt(14)
	ds_write_b128 v202, v[160:163]
	ds_write_b128 v206, v[164:167]
	s_waitcnt vmcnt(13)
	ds_write_b128 v202, v[168:171] offset:9216
	s_waitcnt vmcnt(12)
	ds_write_b128 v202, v[172:175] offset:18432
	s_waitcnt vmcnt(11)
	ds_write_b128 v202, v[176:179] offset:27648
	s_waitcnt vmcnt(10)
	ds_write_b128 v206, v[180:183] offset:9216
	s_waitcnt vmcnt(9)
	ds_write_b128 v206, v[184:187] offset:18432
	s_waitcnt vmcnt(8)
	ds_write_b128 v206, v[188:191] offset:27648
	s_waitcnt lgkmcnt(0)
	v_mfma_f32_16x16x32_bf16 v[136:139], v[214:217], v[222:225], v[136:139]
	s_barrier
	v_mfma_f32_16x16x32_bf16 v[132:135], v[218:221], v[222:225], v[132:135]
	v_mfma_f32_16x16x32_bf16 v[128:131], v[44:47], v[222:225], v[128:131]
	v_mfma_f32_16x16x32_bf16 v[124:127], v[210:213], v[226:229], v[124:127]
	v_mfma_f32_16x16x32_bf16 v[120:123], v[214:217], v[226:229], v[120:123]
	v_mfma_f32_16x16x32_bf16 v[116:119], v[218:221], v[226:229], v[116:119]
	v_mfma_f32_16x16x32_bf16 v[112:115], v[44:47], v[226:229], v[112:115]
	v_mfma_f32_16x16x32_bf16 v[108:111], v[210:213], v[230:233], v[108:111]
	v_mfma_f32_16x16x32_bf16 v[104:107], v[214:217], v[230:233], v[104:107]
	v_mfma_f32_16x16x32_bf16 v[68:71], v[218:221], v[238:241], v[68:71]
	v_mfma_f32_16x16x32_bf16 v[64:67], v[44:47], v[238:241], v[64:67]
	v_mfma_f32_16x16x32_bf16 v[60:63], v[210:213], v[242:245], v[60:63]
	v_mfma_f32_16x16x32_bf16 v[56:59], v[214:217], v[242:245], v[56:59]
	v_mfma_f32_16x16x32_bf16 v[52:55], v[218:221], v[242:245], v[52:55]
	v_mfma_f32_16x16x32_bf16 v[48:51], v[44:47], v[242:245], v[48:51]
	v_mfma_f32_16x16x32_bf16 v[40:43], v[210:213], v[192:195], v[40:43]
	v_mfma_f32_16x16x32_bf16 v[36:39], v[214:217], v[192:195], v[36:39]
	v_mfma_f32_16x16x32_bf16 v[32:35], v[218:221], v[192:195], v[32:35]
	v_mfma_f32_16x16x32_bf16 v[44:47], v[44:47], v[192:195], v[246:249]
	s_cbranch_scc0 .LBB0_1511
	s_cmp_eq_u32 s78, 0
	s_mov_b32 s99, 0x6a44000
	s_cselect_b32 s99, s99, 0x7a44000
	s_lshl_b32 s98, s80, 11
	s_lshl_b32 s100, s79, 1
	s_add_u32 s98, s98, s100
	s_add_u32 s98, s98, s99
	s_add_u32 s100, s34, s98
	s_addc_u32 s101, s35, 0
	v_and_b32_e32 v160, 15, v207
	v_and_b32_e32 v161, 0x80, v203
	v_add_u32_e32 v160, v160, v161
	v_lshlrev_b32_e32 v160, 11, v160
	v_and_b32_e32 v161, 0xc0, v207
	v_lshl_add_u32 v160, v161, 1, v160
	v_and_b32_e32 v161, 4, v203
	v_lshl_add_u32 v160, v161, 3, v160
	v_and_b32_e32 v161, 8, v203
	v_lshl_add_u32 v160, v161, 1, v160
	v_cvt_pk_bf16_f32 v156, v156, v157
	v_cvt_pk_bf16_f32 v157, v158, v159
	v_cvt_pk_bf16_f32 v158, v152, v153
	v_cvt_pk_bf16_f32 v159, v154, v155
	v_cvt_pk_bf16_f32 v148, v148, v149
	v_cvt_pk_bf16_f32 v149, v150, v151
	v_cvt_pk_bf16_f32 v150, v144, v145
	v_cvt_pk_bf16_f32 v151, v146, v147
	v_permlane16_swap_b32_e32 v156, v158
	v_permlane16_swap_b32_e32 v157, v159
	v_permlane16_swap_b32_e32 v148, v150
	v_permlane16_swap_b32_e32 v149, v151
	global_store_dwordx4 v160, v[156:159], s[100:101]
	global_store_dwordx4 v160, v[148:151], s[100:101] offset:64
	s_add_u32 s100, s100, 0x8000
	s_addc_u32 s101, s101, 0
	v_cvt_pk_bf16_f32 v140, v140, v141
	v_cvt_pk_bf16_f32 v141, v142, v143
	v_cvt_pk_bf16_f32 v142, v136, v137
	v_cvt_pk_bf16_f32 v143, v138, v139
	v_cvt_pk_bf16_f32 v132, v132, v133
	v_cvt_pk_bf16_f32 v133, v134, v135
	v_cvt_pk_bf16_f32 v134, v128, v129
	v_cvt_pk_bf16_f32 v135, v130, v131
	v_permlane16_swap_b32_e32 v140, v142
	v_permlane16_swap_b32_e32 v141, v143
	v_permlane16_swap_b32_e32 v132, v134
	v_permlane16_swap_b32_e32 v133, v135
	global_store_dwordx4 v160, v[140:143], s[100:101]
	global_store_dwordx4 v160, v[132:135], s[100:101] offset:64
	s_add_u32 s100, s100, 0x8000
	s_addc_u32 s101, s101, 0
	v_cvt_pk_bf16_f32 v124, v124, v125
	v_cvt_pk_bf16_f32 v125, v126, v127
	v_cvt_pk_bf16_f32 v126, v120, v121
	v_cvt_pk_bf16_f32 v127, v122, v123
	v_cvt_pk_bf16_f32 v116, v116, v117
	v_cvt_pk_bf16_f32 v117, v118, v119
	v_cvt_pk_bf16_f32 v118, v112, v113
	v_cvt_pk_bf16_f32 v119, v114, v115
	v_permlane16_swap_b32_e32 v124, v126
	v_permlane16_swap_b32_e32 v125, v127
	v_permlane16_swap_b32_e32 v116, v118
	v_permlane16_swap_b32_e32 v117, v119
	global_store_dwordx4 v160, v[124:127], s[100:101]
	global_store_dwordx4 v160, v[116:119], s[100:101] offset:64
	s_add_u32 s100, s100, 0x8000
	s_addc_u32 s101, s101, 0
	v_cvt_pk_bf16_f32 v108, v108, v109
	v_cvt_pk_bf16_f32 v109, v110, v111
	v_cvt_pk_bf16_f32 v110, v104, v105
	v_cvt_pk_bf16_f32 v111, v106, v107
	v_cvt_pk_bf16_f32 v100, v100, v101
	v_cvt_pk_bf16_f32 v101, v102, v103
	v_cvt_pk_bf16_f32 v102, v96, v97
	v_cvt_pk_bf16_f32 v103, v98, v99
	v_permlane16_swap_b32_e32 v108, v110
	v_permlane16_swap_b32_e32 v109, v111
	v_permlane16_swap_b32_e32 v100, v102
	v_permlane16_swap_b32_e32 v101, v103
	global_store_dwordx4 v160, v[108:111], s[100:101]
	global_store_dwordx4 v160, v[100:103], s[100:101] offset:64
	s_add_u32 s100, s100, 0x8000
	s_addc_u32 s101, s101, 0
	v_cvt_pk_bf16_f32 v92, v92, v93
	v_cvt_pk_bf16_f32 v93, v94, v95
	v_cvt_pk_bf16_f32 v94, v88, v89
	v_cvt_pk_bf16_f32 v95, v90, v91
	v_cvt_pk_bf16_f32 v80, v80, v81
	v_cvt_pk_bf16_f32 v81, v82, v83
	v_cvt_pk_bf16_f32 v82, v84, v85
	v_cvt_pk_bf16_f32 v83, v86, v87
	v_permlane16_swap_b32_e32 v92, v94
	v_permlane16_swap_b32_e32 v93, v95
	v_permlane16_swap_b32_e32 v80, v82
	v_permlane16_swap_b32_e32 v81, v83
	global_store_dwordx4 v160, v[92:95], s[100:101]
	global_store_dwordx4 v160, v[80:83], s[100:101] offset:64
	s_add_u32 s100, s100, 0x8000
	s_addc_u32 s101, s101, 0
	v_cvt_pk_bf16_f32 v76, v76, v77
	v_cvt_pk_bf16_f32 v77, v78, v79
	v_cvt_pk_bf16_f32 v78, v72, v73
	v_cvt_pk_bf16_f32 v79, v74, v75
	v_cvt_pk_bf16_f32 v68, v68, v69
	v_cvt_pk_bf16_f32 v69, v70, v71
	v_cvt_pk_bf16_f32 v70, v64, v65
	v_cvt_pk_bf16_f32 v71, v66, v67
	v_permlane16_swap_b32_e32 v76, v78
	v_permlane16_swap_b32_e32 v77, v79
	v_permlane16_swap_b32_e32 v68, v70
	v_permlane16_swap_b32_e32 v69, v71
	global_store_dwordx4 v160, v[76:79], s[100:101]
	global_store_dwordx4 v160, v[68:71], s[100:101] offset:64
	s_add_u32 s100, s100, 0x8000
	s_addc_u32 s101, s101, 0
	v_cvt_pk_bf16_f32 v60, v60, v61
	v_cvt_pk_bf16_f32 v61, v62, v63
	v_cvt_pk_bf16_f32 v62, v56, v57
	v_cvt_pk_bf16_f32 v63, v58, v59
	v_cvt_pk_bf16_f32 v52, v52, v53
	v_cvt_pk_bf16_f32 v53, v54, v55
	v_cvt_pk_bf16_f32 v54, v48, v49
	v_cvt_pk_bf16_f32 v55, v50, v51
	v_permlane16_swap_b32_e32 v60, v62
	v_permlane16_swap_b32_e32 v61, v63
	v_permlane16_swap_b32_e32 v52, v54
	v_permlane16_swap_b32_e32 v53, v55
	global_store_dwordx4 v160, v[60:63], s[100:101]
	global_store_dwordx4 v160, v[52:55], s[100:101] offset:64
	s_add_u32 s100, s100, 0x8000
	s_addc_u32 s101, s101, 0
	v_cvt_pk_bf16_f32 v40, v40, v41
	v_cvt_pk_bf16_f32 v41, v42, v43
	v_cvt_pk_bf16_f32 v42, v36, v37
	v_cvt_pk_bf16_f32 v43, v38, v39
	v_cvt_pk_bf16_f32 v32, v32, v33
	v_cvt_pk_bf16_f32 v33, v34, v35
	v_cvt_pk_bf16_f32 v34, v44, v45
	v_cvt_pk_bf16_f32 v35, v46, v47
	v_permlane16_swap_b32_e32 v40, v42
	v_permlane16_swap_b32_e32 v41, v43
	v_permlane16_swap_b32_e32 v32, v34
	v_permlane16_swap_b32_e32 v33, v35
	global_store_dwordx4 v160, v[40:43], s[100:101]
	global_store_dwordx4 v160, v[32:35], s[100:101] offset:64
	s_and_b64 vcc, exec, s[54:55]
	s_mov_b32 s78, s77
	s_mov_b32 s79, s76
	s_mov_b32 s80, s75
	s_mov_b64 s[58:59], s[52:53]
	s_mov_b64 s[56:57], s[50:51]
	s_cbranch_vccz .LBB0_1508
	s_load_dwordx4 s[84:87], s[0:1], 0x100
	s_mov_b64 s[92:93], s[96:97]
